# v8 plus: full cluster barriers issue the invalidate with the first poll; quant_rows ss loads hoisted (no per-row vmcnt(0))
# speedup vs baseline: 1.0314x; 1.0005x over previous
.LBB0_294:
	s_or_b64 exec, exec, s[0:1]
	s_mov_b64 s[0:1], s[82:83]
	v_mov_b32_e32 v2, v0
	s_mov_b32 s5, s72
	s_mov_b32 s2, s73
	s_barrier
	s_load_dwordx2 s[2:3], s[0:1], 0x90
	v_readfirstlane_b32 s4, v2
	s_lshl_b32 s0, s5, 3
	s_and_b32 s0, s0, 56
	s_bfe_u32 s1, s5, 0x30003
	s_ashr_i32 s4, s4, 3
	s_or_b32 s8, s0, s1
	s_and_b32 s1, s5, 0xffffffc0
	s_and_b32 s4, s4, -8
	s_lshl_b32 s0, s8, 8
	s_add_i32 s4, s1, s4
	s_add_i32 s6, s4, s0
	s_ashr_i32 s7, s6, 31
	s_lshl_b64 s[0:1], s[6:7], 11
	v_and_b32_e32 v126, 63, v2
	s_waitcnt lgkmcnt(0)
	s_add_u32 s0, s2, s0
	s_addc_u32 s1, s3, s1
	v_lshlrev_b32_e32 v30, 5, v126
	v_mov_b32_e32 v31, 0
	v_lshl_add_u64 v[2:3], s[0:1], 0, v[30:31]
	s_mov_b32 s0, 0x3001000
	v_add_co_u32_e32 v60, vcc, s0, v2
	s_mov_b64 s[0:1], 0x3000000
	s_nop 0
	v_addc_co_u32_e32 v61, vcc, 0, v3, vcc
	global_load_dwordx4 v[18:21], v[60:61], off offset:-4096
	v_lshl_add_u64 v[4:5], v[2:3], 0, s[0:1]
	global_load_dwordx4 v[22:25], v[4:5], off offset:16
	global_load_dwordx4 v[32:35], v[4:5], off offset:2048
	global_load_dwordx4 v[36:39], v[4:5], off offset:2064
	s_mov_b32 s0, 0x3002000
	v_add_co_u32_e32 v62, vcc, s0, v2
	s_mov_b32 s1, 0x3003000
	s_nop 0
	v_addc_co_u32_e32 v63, vcc, 0, v3, vcc
	v_add_co_u32_e32 v64, vcc, s1, v2
	s_lshl_b32 s5, s8, 19
	s_nop 0
	v_addc_co_u32_e32 v65, vcc, 0, v3, vcc
	global_load_dwordx4 v[40:43], v[60:61], off
	global_load_dwordx4 v[44:47], v[60:61], off offset:16
	global_load_dwordx4 v[48:51], v[60:61], off offset:2048
	global_load_dwordx4 v[52:55], v[60:61], off offset:2064
	global_load_dwordx4 v[56:59], v[64:65], off offset:-4096
	global_load_dwordx4 v[26:29], v[62:63], off offset:16
	global_load_dwordx4 v[14:17], v[62:63], off offset:2048
	global_load_dwordx4 v[10:13], v[62:63], off offset:2064
	global_load_dwordx4 v[6:9], v[64:65], off
	global_load_dwordx4 v[2:5], v[64:65], off offset:16
	s_add_u32 s5, s2, s5
	s_addc_u32 s8, s3, 0
	s_lshl_b32 s4, s4, 10
	s_and_b32 s0, s4, 0x3e000
	s_add_u32 s4, s5, s0
	s_addc_u32 s5, s8, 0
	s_mov_b32 s9, 0x42fe0000
	s_lshl_b64 s[0:1], s[6:7], 2
	s_add_u32 s0, s2, s0
	s_addc_u32 s1, s3, s1
	s_add_u32 s0, s0, 0xfc00000
	s_addc_u32 s1, s1, 0
	s_lshl_b64 s[6:7], s[6:7], 4
	s_mov_b32 s8, 0x40c0c00
	s_add_u32 s2, s2, s6
	s_mov_b32 s6, 0xa800000
	s_addc_u32 s3, s3, s7
	s_add_u32 s2, s2, 0xda00000
	s_addc_u32 s3, s3, 0
	v_mov_b32_e32 v192, 0
	global_load_dwordx4 v[160:163], v192, s[2:3]
	global_load_dwordx4 v[164:167], v192, s[2:3] offset:16
	global_load_dwordx4 v[168:171], v192, s[2:3] offset:32
	global_load_dwordx4 v[172:175], v192, s[2:3] offset:48
	global_load_dwordx4 v[176:179], v192, s[2:3] offset:64
	global_load_dwordx4 v[180:183], v192, s[2:3] offset:80
	global_load_dwordx4 v[184:187], v192, s[2:3] offset:96
	global_load_dwordx4 v[188:191], v192, s[2:3] offset:112
	s_waitcnt vmcnt(12)
	v_lshlrev_b32_e32 v148, 16, v22
	v_lshlrev_b32_e32 v140, 16, v18
	v_and_b32_e32 v141, 0xffff0000, v18
	v_lshlrev_b32_e32 v142, 16, v19
	v_and_b32_e32 v143, 0xffff0000, v19
	v_max3_f32 v18, |v140|, 0, |v141|
	v_lshlrev_b32_e32 v144, 16, v20
	v_and_b32_e32 v145, 0xffff0000, v20
	v_max3_f32 v18, v18, |v142|, |v143|
	v_lshlrev_b32_e32 v146, 16, v21
	v_and_b32_e32 v147, 0xffff0000, v21
	v_max3_f32 v18, v18, |v144|, |v145|
	v_and_b32_e32 v149, 0xffff0000, v22
	v_max3_f32 v18, v18, |v146|, |v147|
	v_lshlrev_b32_e32 v134, 16, v23
	v_and_b32_e32 v132, 0xffff0000, v23
	v_max3_f32 v18, v18, |v148|, |v149|
	v_lshlrev_b32_e32 v150, 16, v24
	v_and_b32_e32 v151, 0xffff0000, v24
	v_max3_f32 v18, v18, |v134|, |v132|
	v_lshlrev_b32_e32 v133, 16, v25
	v_and_b32_e32 v131, 0xffff0000, v25
	v_max3_f32 v18, v18, |v150|, |v151|
	v_max3_f32 v18, v18, |v133|, |v131|
	ds_swizzle_b32 v19, v18 offset:swizzle(SWAP,1)
	s_waitcnt vmcnt(11)
	v_lshlrev_b32_e32 v130, 16, v32
	v_and_b32_e32 v128, 0xffff0000, v32
	v_lshlrev_b32_e32 v122, 16, v33
	v_and_b32_e32 v119, 0xffff0000, v33
	s_waitcnt lgkmcnt(0)
	v_max_f32_e32 v19, v19, v19
	v_max_f32_e32 v18, v18, v19
	ds_swizzle_b32 v19, v18 offset:swizzle(SWAP,2)
	v_max3_f32 v20, |v130|, 0, |v128|
	v_lshlrev_b32_e32 v129, 16, v34
	v_and_b32_e32 v127, 0xffff0000, v34
	v_max3_f32 v20, v20, |v122|, |v119|
	s_waitcnt lgkmcnt(0)
	v_max_f32_e32 v19, v19, v19
	v_max_f32_e32 v18, v18, v19
	ds_swizzle_b32 v19, v18 offset:swizzle(SWAP,4)
	v_lshlrev_b32_e32 v123, 16, v35
	v_and_b32_e32 v121, 0xffff0000, v35
	v_max3_f32 v20, v20, |v129|, |v127|
	s_waitcnt vmcnt(10)
	v_lshlrev_b32_e32 v117, 16, v36
	s_waitcnt lgkmcnt(0)
	v_max_f32_e32 v19, v19, v19
	v_max_f32_e32 v18, v18, v19
	ds_swizzle_b32 v19, v18 offset:swizzle(SWAP,8)
	v_and_b32_e32 v116, 0xffff0000, v36
	v_max3_f32 v20, v20, |v123|, |v121|
	v_lshlrev_b32_e32 v113, 16, v37
	v_and_b32_e32 v114, 0xffff0000, v37
	s_waitcnt lgkmcnt(0)
	v_max_f32_e32 v19, v19, v19
	v_max_f32_e32 v30, v18, v19
	v_max3_f32 v18, v20, |v117|, |v116|
	v_lshlrev_b32_e32 v120, 16, v38
	v_and_b32_e32 v118, 0xffff0000, v38
	v_max3_f32 v18, v18, |v113|, |v114|
	v_lshlrev_b32_e32 v115, 16, v39
	v_and_b32_e32 v112, 0xffff0000, v39
	v_max3_f32 v18, v18, |v120|, |v118|
	ds_swizzle_b32 v32, v30 offset:swizzle(SWAP,16)
	v_max3_f32 v33, v18, |v115|, |v112|
	ds_swizzle_b32 v34, v33 offset:swizzle(SWAP,1)
	s_waitcnt vmcnt(9)
	v_lshlrev_b32_e32 v111, 16, v40
	v_and_b32_e32 v109, 0xffff0000, v40
	s_waitcnt lgkmcnt(1)
	v_max_f32_e32 v32, v32, v32
	v_max_f32_e32 v30, v30, v32
	s_waitcnt lgkmcnt(0)
	v_max_f32_e32 v32, v34, v34
	v_max_f32_e32 v32, v33, v32
	v_lshlrev_b32_e32 v106, 16, v41
	v_and_b32_e32 v105, 0xffff0000, v41
	v_max3_f32 v35, |v111|, 0, |v109|
	global_load_dwordx4 v[22:25], v[64:65], off offset:2048
	global_load_dwordx4 v[18:21], v[64:65], off offset:2064
	ds_swizzle_b32 v33, v32 offset:swizzle(SWAP,2)
	v_lshlrev_b32_e32 v110, 16, v42
	v_and_b32_e32 v108, 0xffff0000, v42
	v_max3_f32 v35, v35, |v106|, |v105|
	v_lshlrev_b32_e32 v107, 16, v43
	v_and_b32_e32 v104, 0xffff0000, v43
	v_max3_f32 v35, v35, |v110|, |v108|
	v_max3_f32 v35, v35, |v107|, |v104|
	s_waitcnt vmcnt(10)
	v_lshlrev_b32_e32 v103, 16, v44
	v_and_b32_e32 v101, 0xffff0000, v44
	v_lshlrev_b32_e32 v99, 16, v45
	v_and_b32_e32 v95, 0xffff0000, v45
	v_max3_f32 v35, v35, |v103|, |v101|
	v_lshlrev_b32_e32 v102, 16, v46
	v_and_b32_e32 v100, 0xffff0000, v46
	v_max3_f32 v35, v35, |v99|, |v95|
	s_waitcnt lgkmcnt(0)
	v_max_f32_e32 v33, v33, v33
	v_lshlrev_b32_e32 v98, 16, v47
	v_and_b32_e32 v94, 0xffff0000, v47
	v_max3_f32 v35, v35, |v102|, |v100|
	v_max_f32_e32 v32, v32, v33
	v_max3_f32 v35, v35, |v98|, |v94|
	ds_swizzle_b32 v33, v32 offset:swizzle(SWAP,4)
	ds_swizzle_b32 v36, v35 offset:swizzle(SWAP,1)
	v_mov_b32_e32 v34, v30
	s_nop 1
	v_permlane32_swap_b32_e32 v30, v34
	s_waitcnt lgkmcnt(1)
	v_max_f32_e32 v33, v33, v33
	s_waitcnt lgkmcnt(0)
	v_max_f32_e32 v36, v36, v36
	v_max_f32_e32 v32, v32, v33
	v_max_f32_e32 v35, v35, v36
	ds_swizzle_b32 v33, v32 offset:swizzle(SWAP,8)
	ds_swizzle_b32 v36, v35 offset:swizzle(SWAP,2)
	v_max_f32_e32 v34, v34, v34
	v_max_f32_e32 v30, v30, v30
	v_max_f32_e32 v137, v30, v34
	s_waitcnt lgkmcnt(1)
	v_max_f32_e32 v30, v33, v33
	s_waitcnt lgkmcnt(0)
	v_max_f32_e32 v33, v36, v36
	s_waitcnt vmcnt(9)
	v_lshlrev_b32_e32 v93, 16, v48
	v_and_b32_e32 v91, 0xffff0000, v48
	v_max_f32_e32 v33, v35, v33
	v_lshlrev_b32_e32 v89, 16, v49
	v_and_b32_e32 v87, 0xffff0000, v49
	v_max3_f32 v35, |v93|, 0, |v91|
	v_lshlrev_b32_e32 v92, 16, v50
	v_and_b32_e32 v90, 0xffff0000, v50
	v_max3_f32 v35, v35, |v89|, |v87|
	v_lshlrev_b32_e32 v88, 16, v51
	v_and_b32_e32 v86, 0xffff0000, v51
	v_max3_f32 v35, v35, |v92|, |v90|
	v_max3_f32 v35, v35, |v88|, |v86|
	s_waitcnt vmcnt(8)
	v_lshlrev_b32_e32 v85, 16, v52
	v_and_b32_e32 v83, 0xffff0000, v52
	v_lshlrev_b32_e32 v81, 16, v53
	v_and_b32_e32 v79, 0xffff0000, v53
	v_max3_f32 v35, v35, |v85|, |v83|
	v_lshlrev_b32_e32 v84, 16, v54
	v_and_b32_e32 v82, 0xffff0000, v54
	v_max3_f32 v35, v35, |v81|, |v79|
	v_lshlrev_b32_e32 v80, 16, v55
	v_and_b32_e32 v78, 0xffff0000, v55
	v_max3_f32 v35, v35, |v84|, |v82|
	ds_swizzle_b32 v34, v33 offset:swizzle(SWAP,4)
	v_max3_f32 v35, v35, |v80|, |v78|
	ds_swizzle_b32 v36, v35 offset:swizzle(SWAP,1)
	v_max_f32_e32 v30, v32, v30
	ds_swizzle_b32 v32, v30 offset:swizzle(SWAP,16)
	s_waitcnt lgkmcnt(2)
	v_max_f32_e32 v34, v34, v34
	v_max_f32_e32 v33, v33, v34
	s_waitcnt lgkmcnt(1)
	v_max_f32_e32 v36, v36, v36
	ds_swizzle_b32 v34, v33 offset:swizzle(SWAP,8)
	v_max_f32_e32 v35, v35, v36
	ds_swizzle_b32 v36, v35 offset:swizzle(SWAP,2)
	s_waitcnt lgkmcnt(2)
	v_max_f32_e32 v32, v32, v32
	v_max_f32_e32 v138, v30, v32
	s_waitcnt lgkmcnt(1)
	v_max_f32_e32 v30, v34, v34
	v_max_f32_e32 v30, v33, v30
	s_waitcnt lgkmcnt(0)
	v_max_f32_e32 v33, v36, v36
	s_waitcnt vmcnt(7)
	v_lshlrev_b32_e32 v77, 16, v56
	v_and_b32_e32 v75, 0xffff0000, v56
	v_max_f32_e32 v33, v35, v33
	v_lshlrev_b32_e32 v72, 16, v57
	v_and_b32_e32 v71, 0xffff0000, v57
	v_max3_f32 v35, |v77|, 0, |v75|
	v_lshlrev_b32_e32 v76, 16, v58
	v_and_b32_e32 v74, 0xffff0000, v58
	v_max3_f32 v35, v35, |v72|, |v71|
	v_lshlrev_b32_e32 v73, 16, v59
	v_and_b32_e32 v70, 0xffff0000, v59
	v_max3_f32 v35, v35, |v76|, |v74|
	v_max3_f32 v35, v35, |v73|, |v70|
	s_waitcnt vmcnt(6)
	v_lshlrev_b32_e32 v69, 16, v26
	v_and_b32_e32 v67, 0xffff0000, v26
	v_lshlrev_b32_e32 v65, 16, v27
	v_and_b32_e32 v63, 0xffff0000, v27
	v_max3_f32 v26, v35, |v69|, |v67|
	v_lshlrev_b32_e32 v68, 16, v28
	v_and_b32_e32 v66, 0xffff0000, v28
	v_max3_f32 v26, v26, |v65|, |v63|
	v_lshlrev_b32_e32 v64, 16, v29
	v_and_b32_e32 v62, 0xffff0000, v29
	v_max3_f32 v26, v26, |v68|, |v66|
	v_max3_f32 v26, v26, |v64|, |v62|
	s_waitcnt vmcnt(5)
	v_lshlrev_b32_e32 v61, 16, v14
	v_and_b32_e32 v59, 0xffff0000, v14
	ds_swizzle_b32 v27, v26 offset:swizzle(SWAP,1)
	v_lshlrev_b32_e32 v57, 16, v15
	v_and_b32_e32 v55, 0xffff0000, v15
	v_max3_f32 v14, |v61|, 0, |v59|
	v_lshlrev_b32_e32 v60, 16, v16
	v_and_b32_e32 v58, 0xffff0000, v16
	v_max3_f32 v14, v14, |v57|, |v55|
	v_lshlrev_b32_e32 v56, 16, v17
	v_and_b32_e32 v54, 0xffff0000, v17
	v_max3_f32 v14, v14, |v60|, |v58|
	v_max3_f32 v14, v14, |v56|, |v54|
	s_waitcnt vmcnt(4)
	v_lshlrev_b32_e32 v53, 16, v10
	v_and_b32_e32 v51, 0xffff0000, v10
	v_lshlrev_b32_e32 v49, 16, v11
	v_and_b32_e32 v47, 0xffff0000, v11
	v_max3_f32 v10, v14, |v53|, |v51|
	s_waitcnt lgkmcnt(0)
	v_max_f32_e32 v27, v27, v27
	v_lshlrev_b32_e32 v52, 16, v12
	v_and_b32_e32 v50, 0xffff0000, v12
	v_max3_f32 v10, v10, |v49|, |v47|
	v_max_f32_e32 v26, v26, v27
	v_lshlrev_b32_e32 v48, 16, v13
	v_and_b32_e32 v46, 0xffff0000, v13
	v_max3_f32 v10, v10, |v52|, |v50|
	ds_swizzle_b32 v27, v26 offset:swizzle(SWAP,2)
	v_max3_f32 v10, v10, |v48|, |v46|
	ds_swizzle_b32 v11, v10 offset:swizzle(SWAP,1)
	ds_swizzle_b32 v34, v33 offset:swizzle(SWAP,4)
	ds_swizzle_b32 v32, v30 offset:swizzle(SWAP,16)
	s_waitcnt lgkmcnt(3)
	v_max_f32_e32 v27, v27, v27
	v_max_f32_e32 v26, v26, v27
	s_waitcnt lgkmcnt(2)
	v_max_f32_e32 v11, v11, v11
	ds_swizzle_b32 v27, v26 offset:swizzle(SWAP,4)
	v_max_f32_e32 v10, v10, v11
	ds_swizzle_b32 v11, v10 offset:swizzle(SWAP,2)
	s_waitcnt lgkmcnt(3)
	v_max_f32_e32 v34, v34, v34
	v_max_f32_e32 v33, v33, v34
	ds_swizzle_b32 v34, v33 offset:swizzle(SWAP,8)
	s_waitcnt lgkmcnt(2)
	v_max_f32_e32 v12, v27, v27
	v_max_f32_e32 v12, v26, v12
	s_waitcnt lgkmcnt(1)
	v_max_f32_e32 v11, v11, v11
	ds_swizzle_b32 v13, v12 offset:swizzle(SWAP,8)
	v_max_f32_e32 v10, v10, v11
	ds_swizzle_b32 v11, v10 offset:swizzle(SWAP,4)
	s_waitcnt lgkmcnt(2)
	v_max_f32_e32 v28, v34, v34
	v_max_f32_e32 v28, v33, v28
	ds_swizzle_b32 v29, v28 offset:swizzle(SWAP,16)
	s_waitcnt lgkmcnt(2)
	v_max_f32_e32 v13, v13, v13
	v_max_f32_e32 v12, v12, v13
	s_waitcnt lgkmcnt(1)
	v_max_f32_e32 v11, v11, v11
	ds_swizzle_b32 v13, v12 offset:swizzle(SWAP,16)
	v_max_f32_e32 v10, v10, v11
	ds_swizzle_b32 v11, v10 offset:swizzle(SWAP,8)
	s_waitcnt vmcnt(3)
	v_lshlrev_b32_e32 v45, 16, v6
	v_and_b32_e32 v43, 0xffff0000, v6
	v_max_f32_e32 v32, v32, v32
	s_waitcnt lgkmcnt(2)
	v_max_f32_e32 v29, v29, v29
	v_lshlrev_b32_e32 v40, 16, v7
	v_and_b32_e32 v39, 0xffff0000, v7
	v_max3_f32 v6, |v45|, 0, |v43|
	s_waitcnt vmcnt(1)
	v_lshlrev_b32_e32 v27, 16, v22
	v_and_b32_e32 v26, 0xffff0000, v22
	v_max_f32_e32 v135, v30, v32
	v_max_f32_e32 v124, v28, v29
	v_lshlrev_b32_e32 v44, 16, v8
	v_and_b32_e32 v42, 0xffff0000, v8
	v_max3_f32 v6, v6, |v40|, |v39|
	v_lshlrev_b32_e32 v32, 16, v5
	v_and_b32_e32 v28, 0xffff0000, v5
	v_lshlrev_b32_e32 v17, 16, v23
	v_and_b32_e32 v15, 0xffff0000, v23
	v_max3_f32 v5, |v27|, 0, |v26|
	v_lshlrev_b32_e32 v41, 16, v9
	v_and_b32_e32 v38, 0xffff0000, v9
	v_max3_f32 v6, v6, |v44|, |v42|
	v_lshlrev_b32_e32 v23, 16, v24
	v_and_b32_e32 v22, 0xffff0000, v24
	v_max3_f32 v5, v5, |v17|, |v15|
	s_waitcnt lgkmcnt(1)
	v_max_f32_e32 v13, v13, v13
	v_max3_f32 v6, v6, |v41|, |v38|
	v_lshlrev_b32_e32 v37, 16, v2
	v_and_b32_e32 v35, 0xffff0000, v2
	v_lshlrev_b32_e32 v16, 16, v25
	v_and_b32_e32 v14, 0xffff0000, v25
	v_max3_f32 v5, v5, |v23|, |v22|
	v_max_f32_e32 v96, v12, v13
	v_lshlrev_b32_e32 v33, 16, v3
	v_and_b32_e32 v29, 0xffff0000, v3
	v_lshlrev_b32_e32 v36, 16, v4
	v_and_b32_e32 v34, 0xffff0000, v4
	v_max3_f32 v2, v6, |v37|, |v35|
	s_waitcnt lgkmcnt(0)
	v_max_f32_e32 v4, v11, v11
	v_max3_f32 v5, v5, |v16|, |v14|
	s_waitcnt vmcnt(0)
	v_lshlrev_b32_e32 v13, 16, v18
	v_and_b32_e32 v11, 0xffff0000, v18
	v_max3_f32 v2, v2, |v33|, |v29|
	v_lshlrev_b32_e32 v9, 16, v19
	v_and_b32_e32 v7, 0xffff0000, v19
	v_max3_f32 v5, v5, |v13|, |v11|
	v_max3_f32 v2, v2, |v36|, |v34|
	v_max_f32_e32 v4, v10, v4
	v_lshlrev_b32_e32 v12, 16, v20
	v_and_b32_e32 v10, 0xffff0000, v20
	v_max3_f32 v5, v5, |v9|, |v7|
	v_max3_f32 v2, v2, |v32|, |v28|
	v_lshlrev_b32_e32 v8, 16, v21
	v_and_b32_e32 v6, 0xffff0000, v21
	v_max3_f32 v5, v5, |v12|, |v10|
	ds_swizzle_b32 v3, v2 offset:swizzle(SWAP,1)
	v_max3_f32 v5, v5, |v8|, |v6|
	ds_swizzle_b32 v18, v5 offset:swizzle(SWAP,1)
	ds_swizzle_b32 v19, v4 offset:swizzle(SWAP,16)
	v_lshlrev_b32_e32 v30, 4, v126
	s_waitcnt lgkmcnt(2)
	v_max_f32_e32 v3, v3, v3
	v_max_f32_e32 v2, v2, v3
	s_waitcnt lgkmcnt(1)
	v_max_f32_e32 v18, v18, v18
	ds_swizzle_b32 v3, v2 offset:swizzle(SWAP,2)
	v_max_f32_e32 v5, v5, v18
	ds_swizzle_b32 v18, v5 offset:swizzle(SWAP,2)
	s_waitcnt lgkmcnt(2)
	v_max_f32_e32 v19, v19, v19
	v_max_f32_e32 v24, v4, v19
	s_waitcnt lgkmcnt(1)
	v_max_f32_e32 v3, v3, v3
	v_max_f32_e32 v2, v2, v3
	s_waitcnt lgkmcnt(0)
	v_max_f32_e32 v18, v18, v18
	ds_swizzle_b32 v3, v2 offset:swizzle(SWAP,4)
	v_max_f32_e32 v5, v5, v18
	ds_swizzle_b32 v18, v5 offset:swizzle(SWAP,4)
	v_mov_b32_e32 v139, v138
	v_mov_b32_e32 v136, v135
	s_waitcnt lgkmcnt(1)
	v_max_f32_e32 v3, v3, v3
	v_max_f32_e32 v2, v2, v3
	s_waitcnt lgkmcnt(0)
	v_max_f32_e32 v4, v18, v18
	ds_swizzle_b32 v3, v2 offset:swizzle(SWAP,8)
	v_max_f32_e32 v4, v5, v4
	ds_swizzle_b32 v5, v4 offset:swizzle(SWAP,8)
	v_mov_b32_e32 v125, v124
	v_mov_b32_e32 v97, v96
	s_waitcnt lgkmcnt(1)
	v_max_f32_e32 v3, v3, v3
	v_max_f32_e32 v2, v2, v3
	s_waitcnt lgkmcnt(0)
	v_max_f32_e32 v5, v5, v5
	ds_swizzle_b32 v3, v2 offset:swizzle(SWAP,16)
	v_max_f32_e32 v4, v4, v5
	ds_swizzle_b32 v5, v4 offset:swizzle(SWAP,16)
	v_mov_b32_e32 v25, v24
	v_permlane32_swap_b32_e32 v138, v139
	s_waitcnt lgkmcnt(1)
	v_max_f32_e32 v3, v3, v3
	v_max_f32_e32 v20, v2, v3
	s_waitcnt lgkmcnt(0)
	v_max_f32_e32 v2, v5, v5
	v_max_f32_e32 v18, v4, v2
	v_lshl_add_u64 v[4:5], s[4:5], 0, v[30:31]
	v_div_scale_f32 v30, s[4:5], v137, v137, s9
	v_rcp_f32_e32 v152, v30
	s_mov_b64 s[4:5], 0xa800000
	v_lshl_add_u64 v[2:3], v[4:5], 0, s[4:5]
	v_cmp_eq_u32_e64 s[4:5], 0, v126
	v_fma_f32 v126, -v30, v152, 1.0
	v_fmac_f32_e32 v152, v126, v152
	v_div_scale_f32 v126, vcc, s9, v137, s9
	v_mul_f32_e32 v153, v126, v152
	v_fma_f32 v154, -v30, v153, v126
	v_fmac_f32_e32 v153, v154, v152
	v_fma_f32 v30, -v30, v153, v126
	v_div_fmas_f32 v30, v30, v152, v153
	v_div_fixup_f32 v30, v30, v137, s9
	v_cmp_lt_f32_e32 vcc, 0, v137
	v_mov_b32_e32 v21, v20
	v_mov_b32_e32 v19, v18
	v_cndmask_b32_e32 v30, 0, v30, vcc
	v_mul_f32_e32 v126, v30, v140
	v_mul_f32_e32 v140, v30, v141
	v_rndne_f32_e32 v140, v140
	v_mul_f32_e32 v141, v30, v144
	v_mul_f32_e32 v144, v30, v145
	v_mul_f32_e32 v142, v30, v142
	v_mul_f32_e32 v143, v30, v143
	v_rndne_f32_e32 v126, v126
	v_cvt_i32_f32_e32 v140, v140
	v_rndne_f32_e32 v144, v144
	v_rndne_f32_e32 v142, v142
	v_mul_f32_e32 v145, v30, v146
	v_rndne_f32_e32 v143, v143
	v_mul_f32_e32 v146, v30, v147
	v_cvt_i32_f32_e32 v126, v126
	v_rndne_f32_e32 v141, v141
	v_cvt_i32_f32_e32 v144, v144
	v_cvt_i32_f32_sdwa v142, v142 dst_sel:WORD_1 dst_unused:UNUSED_PAD src0_sel:DWORD
	v_rndne_f32_e32 v145, v145
	v_cvt_i32_f32_e32 v143, v143
	v_rndne_f32_e32 v146, v146
	v_cvt_i32_f32_e32 v141, v141
	v_cvt_i32_f32_sdwa v145, v145 dst_sel:WORD_1 dst_unused:UNUSED_PAD src0_sel:DWORD
	v_cvt_i32_f32_e32 v146, v146
	v_lshlrev_b32_e32 v140, 8, v140
	v_and_b32_e32 v140, 0xff00, v140
	v_lshlrev_b32_e32 v144, 8, v144
	v_and_b32_e32 v142, 0xff0000, v142
	v_perm_b32 v126, v143, v126, s8
	v_and_b32_e32 v144, 0xff00, v144
	v_and_b32_e32 v145, 0xff0000, v145
	v_or3_b32 v140, v126, v140, v142
	v_perm_b32 v126, v146, v141, s8
	v_add_co_u32_e32 v4, vcc, s6, v4
	v_or3_b32 v141, v126, v144, v145
	s_nop 0
	v_addc_co_u32_e32 v5, vcc, 0, v5, vcc
	v_mov_b32_e32 v200, v140
	v_mov_b32_e32 v201, v141
	v_mul_f32_e32 v5, v30, v149
	v_mul_f32_e32 v4, v30, v148
	v_rndne_f32_e32 v5, v5
	v_mul_f32_e32 v140, v30, v151
	v_mul_f32_e32 v134, v30, v134
	v_mul_f32_e32 v132, v30, v132
	v_rndne_f32_e32 v4, v4
	v_cvt_i32_f32_e32 v5, v5
	v_mul_f32_e32 v126, v30, v150
	v_rndne_f32_e32 v140, v140
	v_rndne_f32_e32 v134, v134
	v_mul_f32_e32 v133, v30, v133
	v_rndne_f32_e32 v132, v132
	v_mul_f32_e32 v30, v30, v131
	v_cvt_i32_f32_e32 v4, v4
	v_rndne_f32_e32 v126, v126
	v_cvt_i32_f32_e32 v140, v140
	v_cvt_i32_f32_sdwa v134, v134 dst_sel:WORD_1 dst_unused:UNUSED_PAD src0_sel:DWORD
	v_rndne_f32_e32 v133, v133
	v_cvt_i32_f32_e32 v132, v132
	v_rndne_f32_e32 v30, v30
	v_cvt_i32_f32_e32 v126, v126
	v_cvt_i32_f32_sdwa v133, v133 dst_sel:WORD_1 dst_unused:UNUSED_PAD src0_sel:DWORD
	v_cvt_i32_f32_e32 v30, v30
	v_lshlrev_b32_e32 v5, 8, v5
	v_and_b32_e32 v5, 0xff00, v5
	v_lshlrev_b32_e32 v140, 8, v140
	v_and_b32_e32 v134, 0xff0000, v134
	v_perm_b32 v4, v132, v4, s8
	v_and_b32_e32 v140, 0xff00, v140
	v_and_b32_e32 v131, 0xff0000, v133
	v_or3_b32 v4, v4, v5, v134
	v_perm_b32 v5, v30, v126, s8
	v_permlane32_swap_b32_e32 v135, v136
	v_permlane32_swap_b32_e32 v124, v125
	v_permlane32_swap_b32_e32 v96, v97
	v_permlane32_swap_b32_e32 v24, v25
	v_permlane32_swap_b32_e32 v20, v21
	v_permlane32_swap_b32_e32 v18, v19
	v_or3_b32 v5, v5, v140, v131
	v_mov_b32_e32 v202, v4
	v_mov_b32_e32 v203, v5
	global_store_dwordx4 v[2:3], v[200:203], off
	s_and_saveexec_b64 s[6:7], s[4:5]
	s_cbranch_execz .LBB0_296
	v_mov_b32_e32 v140, v160
	v_mov_b32_e32 v141, v161
	v_mov_b32_e32 v142, v162
	v_mov_b32_e32 v143, v163
	v_mov_b32_e32 v4, v141
	v_mov_b32_e32 v5, v142
	v_mov_b32_e32 v141, v143
	v_pk_add_f32 v[4:5], v[4:5], v[140:141]
	s_nop 0
	v_add_f32_e32 v4, v4, v5
	v_mov_b32_e32 v5, 0x358637bd
	v_fmac_f32_e32 v5, 0x3a800000, v4
	v_rsq_f32_e32 v4, v5
	v_mul_f32_e32 v5, 0x3c010204, v137
	v_mul_f32_e32 v4, v5, v4
	global_store_dword v31, v4, s[0:1]
.LBB0_296:
	s_or_b64 exec, exec, s[6:7]
	v_max_f32_e32 v4, v138, v138
	v_max_f32_e32 v5, v139, v139
	v_max_f32_e32 v4, v4, v5
	v_div_scale_f32 v5, s[6:7], v4, v4, s9
	v_rcp_f32_e32 v30, v5
	s_nop 0
	v_fma_f32 v31, -v5, v30, 1.0
	v_fmac_f32_e32 v30, v31, v30
	v_div_scale_f32 v31, vcc, s9, v4, s9
	v_mul_f32_e32 v126, v31, v30
	v_fma_f32 v131, -v5, v126, v31
	v_fmac_f32_e32 v126, v131, v30
	v_fma_f32 v5, -v5, v126, v31
	v_div_fmas_f32 v5, v5, v30, v126
	v_div_fixup_f32 v5, v5, v4, s9
	v_cmp_lt_f32_e32 vcc, 0, v4
	s_nop 1
	v_cndmask_b32_e32 v5, 0, v5, vcc
	v_mul_f32_e32 v31, v5, v128
	v_mul_f32_e32 v30, v5, v130
	v_rndne_f32_e32 v31, v31
	v_mul_f32_e32 v127, v5, v127
	v_mul_f32_e32 v122, v5, v122
	v_mul_f32_e32 v119, v5, v119
	v_rndne_f32_e32 v30, v30
	v_cvt_i32_f32_e32 v31, v31
	v_mul_f32_e32 v126, v5, v129
	v_rndne_f32_e32 v127, v127
	v_rndne_f32_e32 v122, v122
	v_mul_f32_e32 v123, v5, v123
	v_rndne_f32_e32 v119, v119
	v_mul_f32_e32 v121, v5, v121
	v_cvt_i32_f32_e32 v30, v30
	v_rndne_f32_e32 v126, v126
	v_cvt_i32_f32_e32 v127, v127
	v_cvt_i32_f32_sdwa v122, v122 dst_sel:WORD_1 dst_unused:UNUSED_PAD src0_sel:DWORD
	v_rndne_f32_e32 v123, v123
	v_cvt_i32_f32_e32 v119, v119
	v_rndne_f32_e32 v121, v121
	v_cvt_i32_f32_e32 v126, v126
	v_cvt_i32_f32_sdwa v123, v123 dst_sel:WORD_1 dst_unused:UNUSED_PAD src0_sel:DWORD
	v_cvt_i32_f32_e32 v121, v121
	v_lshlrev_b32_e32 v31, 8, v31
	v_and_b32_e32 v31, 0xff00, v31
	v_lshlrev_b32_e32 v127, 8, v127
	v_and_b32_e32 v122, 0xff0000, v122
	v_perm_b32 v30, v119, v30, s8
	v_and_b32_e32 v127, 0xff00, v127
	v_and_b32_e32 v123, 0xff0000, v123
	v_or3_b32 v30, v30, v31, v122
	v_perm_b32 v31, v121, v126, s8
	v_or3_b32 v31, v31, v127, v123
	v_mov_b32_e32 v204, v30
	v_mov_b32_e32 v205, v31
	v_mul_f32_e32 v30, v5, v117
	v_mul_f32_e32 v31, v5, v116
	v_mul_f32_e32 v117, v5, v118
	v_rndne_f32_e32 v31, v31
	v_mul_f32_e32 v116, v5, v120
	v_rndne_f32_e32 v117, v117
	v_mul_f32_e32 v113, v5, v113
	v_mul_f32_e32 v115, v5, v115
	v_mul_f32_e32 v114, v5, v114
	v_mul_f32_e32 v5, v5, v112
	v_rndne_f32_e32 v30, v30
	v_cvt_i32_f32_e32 v31, v31
	v_rndne_f32_e32 v116, v116
	v_cvt_i32_f32_e32 v117, v117
	v_rndne_f32_e32 v113, v113
	v_rndne_f32_e32 v115, v115
	v_rndne_f32_e32 v114, v114
	v_rndne_f32_e32 v5, v5
	v_cvt_i32_f32_e32 v30, v30
	v_cvt_i32_f32_e32 v116, v116
	v_cvt_i32_f32_sdwa v113, v113 dst_sel:WORD_1 dst_unused:UNUSED_PAD src0_sel:DWORD
	v_cvt_i32_f32_sdwa v115, v115 dst_sel:WORD_1 dst_unused:UNUSED_PAD src0_sel:DWORD
	v_cvt_i32_f32_e32 v114, v114
	v_cvt_i32_f32_e32 v5, v5
	v_lshlrev_b32_e32 v31, 8, v31
	v_lshlrev_b32_e32 v117, 8, v117
	v_and_b32_e32 v31, 0xff00, v31
	v_and_b32_e32 v117, 0xff00, v117
	v_and_b32_e32 v113, 0xff0000, v113
	v_and_b32_e32 v112, 0xff0000, v115
	v_perm_b32 v30, v114, v30, s8
	v_perm_b32 v5, v5, v116, s8
	v_or3_b32 v30, v30, v31, v113
	v_or3_b32 v31, v5, v117, v112
	v_mov_b32_e32 v206, v30
	v_mov_b32_e32 v207, v31
	global_store_dwordx4 v[2:3], v[204:207], off offset:1024
	s_and_saveexec_b64 s[6:7], s[4:5]
	s_cbranch_execz .LBB0_298
	v_mov_b32_e32 v5, 0
	v_mov_b32_e32 v112, v164
	v_mov_b32_e32 v113, v165
	v_mov_b32_e32 v114, v166
	v_mov_b32_e32 v115, v167
	v_mul_f32_e32 v4, 0x3c010204, v4
	v_mov_b32_e32 v30, v113
	v_mov_b32_e32 v31, v114
	v_mov_b32_e32 v113, v115
	v_pk_add_f32 v[30:31], v[30:31], v[112:113]
	s_nop 0
	v_add_f32_e32 v30, v30, v31
	v_mov_b32_e32 v31, 0x358637bd
	v_fmac_f32_e32 v31, 0x3a800000, v30
	v_rsq_f32_e32 v30, v31
	s_nop 0
	v_mul_f32_e32 v4, v4, v30
	global_store_dword v5, v4, s[0:1] offset:4
.LBB0_298:
	s_or_b64 exec, exec, s[6:7]
	v_max_f32_e32 v4, v135, v135
	v_max_f32_e32 v5, v136, v136
	v_max_f32_e32 v4, v4, v5
	v_div_scale_f32 v5, s[6:7], v4, v4, s9
	v_rcp_f32_e32 v30, v5
	s_nop 0
	v_fma_f32 v31, -v5, v30, 1.0
	v_fmac_f32_e32 v30, v31, v30
	v_div_scale_f32 v31, vcc, s9, v4, s9
	v_mul_f32_e32 v112, v31, v30
	v_fma_f32 v113, -v5, v112, v31
	v_fmac_f32_e32 v112, v113, v30
	v_fma_f32 v5, -v5, v112, v31
	v_div_fmas_f32 v5, v5, v30, v112
	v_div_fixup_f32 v5, v5, v4, s9
	v_cmp_lt_f32_e32 vcc, 0, v4
	s_nop 1
	v_cndmask_b32_e32 v5, 0, v5, vcc
	v_mul_f32_e32 v31, v5, v109
	v_mul_f32_e32 v30, v5, v111
	v_rndne_f32_e32 v31, v31
	v_mul_f32_e32 v108, v5, v108
	v_mul_f32_e32 v106, v5, v106
	v_mul_f32_e32 v105, v5, v105
	v_rndne_f32_e32 v30, v30
	v_cvt_i32_f32_e32 v31, v31
	v_mul_f32_e32 v109, v5, v110
	v_rndne_f32_e32 v108, v108
	v_rndne_f32_e32 v106, v106
	v_mul_f32_e32 v107, v5, v107
	v_rndne_f32_e32 v105, v105
	v_mul_f32_e32 v104, v5, v104
	v_cvt_i32_f32_e32 v30, v30
	v_rndne_f32_e32 v109, v109
	v_cvt_i32_f32_e32 v108, v108
	v_cvt_i32_f32_sdwa v106, v106 dst_sel:WORD_1 dst_unused:UNUSED_PAD src0_sel:DWORD
	v_rndne_f32_e32 v107, v107
	v_cvt_i32_f32_e32 v105, v105
	v_rndne_f32_e32 v104, v104
	v_cvt_i32_f32_e32 v109, v109
	v_cvt_i32_f32_sdwa v107, v107 dst_sel:WORD_1 dst_unused:UNUSED_PAD src0_sel:DWORD
	v_cvt_i32_f32_e32 v104, v104
	v_lshlrev_b32_e32 v31, 8, v31
	v_and_b32_e32 v31, 0xff00, v31
	v_lshlrev_b32_e32 v108, 8, v108
	v_and_b32_e32 v106, 0xff0000, v106
	v_perm_b32 v30, v105, v30, s8
	v_and_b32_e32 v108, 0xff00, v108
	v_and_b32_e32 v107, 0xff0000, v107
	v_or3_b32 v30, v30, v31, v106
	v_perm_b32 v31, v104, v109, s8
	v_or3_b32 v31, v31, v108, v107
	v_mov_b32_e32 v200, v30
	v_mov_b32_e32 v201, v31
	v_mul_f32_e32 v31, v5, v101
	v_mul_f32_e32 v100, v5, v100
	v_mul_f32_e32 v30, v5, v103
	v_rndne_f32_e32 v31, v31
	v_mul_f32_e32 v101, v5, v102
	v_rndne_f32_e32 v100, v100
	v_mul_f32_e32 v99, v5, v99
	v_mul_f32_e32 v98, v5, v98
	v_mul_f32_e32 v95, v5, v95
	v_mul_f32_e32 v5, v5, v94
	v_rndne_f32_e32 v30, v30
	v_cvt_i32_f32_e32 v31, v31
	v_rndne_f32_e32 v101, v101
	v_cvt_i32_f32_e32 v100, v100
	v_rndne_f32_e32 v99, v99
	v_rndne_f32_e32 v98, v98
	v_rndne_f32_e32 v95, v95
	v_rndne_f32_e32 v5, v5
	v_cvt_i32_f32_e32 v30, v30
	v_cvt_i32_f32_e32 v101, v101
	v_cvt_i32_f32_sdwa v99, v99 dst_sel:WORD_1 dst_unused:UNUSED_PAD src0_sel:DWORD
	v_cvt_i32_f32_sdwa v98, v98 dst_sel:WORD_1 dst_unused:UNUSED_PAD src0_sel:DWORD
	v_cvt_i32_f32_e32 v95, v95
	v_cvt_i32_f32_e32 v5, v5
	v_lshlrev_b32_e32 v31, 8, v31
	v_lshlrev_b32_e32 v100, 8, v100
	v_and_b32_e32 v31, 0xff00, v31
	v_and_b32_e32 v100, 0xff00, v100
	v_and_b32_e32 v99, 0xff0000, v99
	v_and_b32_e32 v94, 0xff0000, v98
	v_perm_b32 v30, v95, v30, s8
	v_perm_b32 v5, v5, v101, s8
	v_or3_b32 v30, v30, v31, v99
	v_or3_b32 v31, v5, v100, v94
	v_mov_b32_e32 v202, v30
	v_mov_b32_e32 v203, v31
	global_store_dwordx4 v[2:3], v[200:203], off offset:2048
	s_and_saveexec_b64 s[6:7], s[4:5]
	s_cbranch_execz .LBB0_300
	v_mov_b32_e32 v5, 0
	v_mov_b32_e32 v98, v168
	v_mov_b32_e32 v99, v169
	v_mov_b32_e32 v100, v170
	v_mov_b32_e32 v101, v171
	v_mul_f32_e32 v4, 0x3c010204, v4
	v_mov_b32_e32 v30, v99
	v_mov_b32_e32 v31, v100
	v_mov_b32_e32 v99, v101
	v_pk_add_f32 v[30:31], v[30:31], v[98:99]
	s_nop 0
	v_add_f32_e32 v30, v30, v31
	v_mov_b32_e32 v31, 0x358637bd
	v_fmac_f32_e32 v31, 0x3a800000, v30
	v_rsq_f32_e32 v30, v31
	s_nop 0
	v_mul_f32_e32 v4, v4, v30
	global_store_dword v5, v4, s[0:1] offset:8
.LBB0_300:
	s_or_b64 exec, exec, s[6:7]
	v_max_f32_e32 v4, v124, v124
	v_max_f32_e32 v5, v125, v125
	v_max_f32_e32 v4, v4, v5
	v_div_scale_f32 v5, s[6:7], v4, v4, s9
	v_rcp_f32_e32 v30, v5
	s_nop 0
	v_fma_f32 v31, -v5, v30, 1.0
	v_fmac_f32_e32 v30, v31, v30
	v_div_scale_f32 v31, vcc, s9, v4, s9
	v_mul_f32_e32 v94, v31, v30
	v_fma_f32 v95, -v5, v94, v31
	v_fmac_f32_e32 v94, v95, v30
	v_fma_f32 v5, -v5, v94, v31
	v_div_fmas_f32 v5, v5, v30, v94
	v_div_fixup_f32 v5, v5, v4, s9
	v_cmp_lt_f32_e32 vcc, 0, v4
	s_nop 1
	v_cndmask_b32_e32 v5, 0, v5, vcc
	v_mul_f32_e32 v31, v5, v91
	v_mul_f32_e32 v30, v5, v93
	v_rndne_f32_e32 v31, v31
	v_mul_f32_e32 v90, v5, v90
	v_mul_f32_e32 v89, v5, v89
	v_mul_f32_e32 v87, v5, v87
	v_rndne_f32_e32 v30, v30
	v_cvt_i32_f32_e32 v31, v31
	v_mul_f32_e32 v91, v5, v92
	v_rndne_f32_e32 v90, v90
	v_rndne_f32_e32 v89, v89
	v_mul_f32_e32 v88, v5, v88
	v_rndne_f32_e32 v87, v87
	v_mul_f32_e32 v86, v5, v86
	v_cvt_i32_f32_e32 v30, v30
	v_rndne_f32_e32 v91, v91
	v_cvt_i32_f32_e32 v90, v90
	v_cvt_i32_f32_sdwa v89, v89 dst_sel:WORD_1 dst_unused:UNUSED_PAD src0_sel:DWORD
	v_rndne_f32_e32 v88, v88
	v_cvt_i32_f32_e32 v87, v87
	v_rndne_f32_e32 v86, v86
	v_cvt_i32_f32_e32 v91, v91
	v_cvt_i32_f32_sdwa v88, v88 dst_sel:WORD_1 dst_unused:UNUSED_PAD src0_sel:DWORD
	v_cvt_i32_f32_e32 v86, v86
	v_lshlrev_b32_e32 v31, 8, v31
	v_and_b32_e32 v31, 0xff00, v31
	v_lshlrev_b32_e32 v90, 8, v90
	v_and_b32_e32 v89, 0xff0000, v89
	v_perm_b32 v30, v87, v30, s8
	v_and_b32_e32 v90, 0xff00, v90
	v_and_b32_e32 v88, 0xff0000, v88
	v_or3_b32 v30, v30, v31, v89
	v_perm_b32 v31, v86, v91, s8
	v_or3_b32 v31, v31, v90, v88
	v_mov_b32_e32 v204, v30
	v_mov_b32_e32 v205, v31
	v_mul_f32_e32 v31, v5, v83
	v_mul_f32_e32 v82, v5, v82
	v_mul_f32_e32 v30, v5, v85
	v_rndne_f32_e32 v31, v31
	v_mul_f32_e32 v83, v5, v84
	v_rndne_f32_e32 v82, v82
	v_mul_f32_e32 v81, v5, v81
	v_mul_f32_e32 v80, v5, v80
	v_mul_f32_e32 v79, v5, v79
	v_mul_f32_e32 v5, v5, v78
	v_rndne_f32_e32 v30, v30
	v_cvt_i32_f32_e32 v31, v31
	v_rndne_f32_e32 v83, v83
	v_cvt_i32_f32_e32 v82, v82
	v_rndne_f32_e32 v81, v81
	v_rndne_f32_e32 v80, v80
	v_rndne_f32_e32 v79, v79
	v_rndne_f32_e32 v5, v5
	v_cvt_i32_f32_e32 v30, v30
	v_cvt_i32_f32_e32 v83, v83
	v_cvt_i32_f32_sdwa v81, v81 dst_sel:WORD_1 dst_unused:UNUSED_PAD src0_sel:DWORD
	v_cvt_i32_f32_sdwa v80, v80 dst_sel:WORD_1 dst_unused:UNUSED_PAD src0_sel:DWORD
	v_cvt_i32_f32_e32 v79, v79
	v_cvt_i32_f32_e32 v5, v5
	v_lshlrev_b32_e32 v31, 8, v31
	v_lshlrev_b32_e32 v82, 8, v82
	v_and_b32_e32 v31, 0xff00, v31
	v_and_b32_e32 v82, 0xff00, v82
	v_and_b32_e32 v81, 0xff0000, v81
	v_and_b32_e32 v78, 0xff0000, v80
	v_perm_b32 v30, v79, v30, s8
	v_perm_b32 v5, v5, v83, s8
	v_or3_b32 v30, v30, v31, v81
	v_or3_b32 v31, v5, v82, v78
	v_mov_b32_e32 v206, v30
	v_mov_b32_e32 v207, v31
	global_store_dwordx4 v[2:3], v[204:207], off offset:3072
	s_and_saveexec_b64 s[6:7], s[4:5]
	s_cbranch_execz .LBB0_302
	v_mov_b32_e32 v5, 0
	v_mov_b32_e32 v78, v172
	v_mov_b32_e32 v79, v173
	v_mov_b32_e32 v80, v174
	v_mov_b32_e32 v81, v175
	v_mul_f32_e32 v4, 0x3c010204, v4
	v_mov_b32_e32 v30, v79
	v_mov_b32_e32 v31, v80
	v_mov_b32_e32 v79, v81
	v_pk_add_f32 v[30:31], v[30:31], v[78:79]
	s_nop 0
	v_add_f32_e32 v30, v30, v31
	v_mov_b32_e32 v31, 0x358637bd
	v_fmac_f32_e32 v31, 0x3a800000, v30
	v_rsq_f32_e32 v30, v31
	s_nop 0
	v_mul_f32_e32 v4, v4, v30
	global_store_dword v5, v4, s[0:1] offset:12
.LBB0_302:
	s_or_b64 exec, exec, s[6:7]
	v_max_f32_e32 v4, v96, v96
	v_max_f32_e32 v5, v97, v97
	v_max_f32_e32 v30, v4, v5
	v_div_scale_f32 v4, s[6:7], v30, v30, s9
	v_rcp_f32_e32 v5, v4
	s_movk_i32 s6, 0x1000
	v_fma_f32 v31, -v4, v5, 1.0
	v_fmac_f32_e32 v5, v31, v5
	v_div_scale_f32 v31, vcc, s9, v30, s9
	v_mul_f32_e32 v78, v31, v5
	v_fma_f32 v79, -v4, v78, v31
	v_fmac_f32_e32 v78, v79, v5
	v_fma_f32 v4, -v4, v78, v31
	v_div_fmas_f32 v4, v4, v5, v78
	v_div_fixup_f32 v4, v4, v30, s9
	v_cmp_lt_f32_e32 vcc, 0, v30
	s_nop 1
	v_cndmask_b32_e32 v31, 0, v4, vcc
	v_mul_f32_e32 v5, v31, v75
	v_mul_f32_e32 v4, v31, v77
	v_rndne_f32_e32 v5, v5
	v_mul_f32_e32 v74, v31, v74
	v_mul_f32_e32 v72, v31, v72
	v_mul_f32_e32 v71, v31, v71
	v_rndne_f32_e32 v4, v4
	v_cvt_i32_f32_e32 v5, v5
	v_mul_f32_e32 v75, v31, v76
	v_rndne_f32_e32 v74, v74
	v_rndne_f32_e32 v72, v72
	v_mul_f32_e32 v73, v31, v73
	v_rndne_f32_e32 v71, v71
	v_mul_f32_e32 v70, v31, v70
	v_mul_f32_e32 v67, v31, v67
	v_mul_f32_e32 v66, v31, v66
	v_cvt_i32_f32_e32 v4, v4
	v_rndne_f32_e32 v75, v75
	v_cvt_i32_f32_e32 v74, v74
	v_cvt_i32_f32_sdwa v72, v72 dst_sel:WORD_1 dst_unused:UNUSED_PAD src0_sel:DWORD
	v_rndne_f32_e32 v73, v73
	v_cvt_i32_f32_e32 v71, v71
	v_rndne_f32_e32 v70, v70
	v_mul_f32_e32 v69, v31, v69
	v_rndne_f32_e32 v67, v67
	v_mul_f32_e32 v68, v31, v68
	v_rndne_f32_e32 v66, v66
	v_mul_f32_e32 v65, v31, v65
	v_mul_f32_e32 v64, v31, v64
	v_mul_f32_e32 v63, v31, v63
	v_mul_f32_e32 v31, v31, v62
	v_cvt_i32_f32_e32 v75, v75
	v_cvt_i32_f32_sdwa v73, v73 dst_sel:WORD_1 dst_unused:UNUSED_PAD src0_sel:DWORD
	v_cvt_i32_f32_e32 v76, v70
	v_rndne_f32_e32 v69, v69
	v_cvt_i32_f32_e32 v67, v67
	v_rndne_f32_e32 v68, v68
	v_cvt_i32_f32_e32 v66, v66
	v_rndne_f32_e32 v65, v65
	v_rndne_f32_e32 v64, v64
	v_rndne_f32_e32 v63, v63
	v_rndne_f32_e32 v31, v31
	v_cvt_i32_f32_e32 v69, v69
	v_cvt_i32_f32_e32 v68, v68
	v_cvt_i32_f32_sdwa v65, v65 dst_sel:WORD_1 dst_unused:UNUSED_PAD src0_sel:DWORD
	v_cvt_i32_f32_sdwa v64, v64 dst_sel:WORD_1 dst_unused:UNUSED_PAD src0_sel:DWORD
	v_cvt_i32_f32_e32 v63, v63
	v_cvt_i32_f32_e32 v31, v31
	v_lshlrev_b32_e32 v5, 8, v5
	v_and_b32_e32 v5, 0xff00, v5
	v_lshlrev_b32_e32 v74, 8, v74
	v_and_b32_e32 v72, 0xff0000, v72
	v_perm_b32 v4, v71, v4, s8
	v_and_b32_e32 v74, 0xff00, v74
	v_and_b32_e32 v73, 0xff0000, v73
	v_or3_b32 v70, v4, v5, v72
	v_perm_b32 v4, v76, v75, s8
	v_lshlrev_b32_e32 v67, 8, v67
	v_lshlrev_b32_e32 v66, 8, v66
	v_or3_b32 v71, v4, v74, v73
	v_add_co_u32_e32 v4, vcc, s6, v2
	v_and_b32_e32 v67, 0xff00, v67
	v_and_b32_e32 v66, 0xff00, v66
	v_and_b32_e32 v65, 0xff0000, v65
	v_and_b32_e32 v64, 0xff0000, v64
	v_perm_b32 v62, v63, v69, s8
	v_perm_b32 v31, v31, v68, s8
	v_addc_co_u32_e32 v5, vcc, 0, v3, vcc
	v_or3_b32 v62, v62, v67, v65
	v_or3_b32 v63, v31, v66, v64
	v_mov_b32_e32 v200, v70
	v_mov_b32_e32 v201, v71
	v_mov_b32_e32 v202, v62
	v_mov_b32_e32 v203, v63
	global_store_dwordx4 v[4:5], v[200:203], off
	s_and_saveexec_b64 s[6:7], s[4:5]
	s_cbranch_execz .LBB0_304
	v_mov_b32_e32 v31, 0
	v_mov_b32_e32 v62, v176
	v_mov_b32_e32 v63, v177
	v_mov_b32_e32 v64, v178
	v_mov_b32_e32 v65, v179
	v_mul_f32_e32 v30, 0x3c010204, v30
	v_mov_b32_e32 v66, v63
	v_mov_b32_e32 v67, v64
	v_mov_b32_e32 v63, v65
	v_pk_add_f32 v[62:63], v[66:67], v[62:63]
	s_nop 0
	v_add_f32_e32 v62, v62, v63
	v_mov_b32_e32 v63, 0x358637bd
	v_fmac_f32_e32 v63, 0x3a800000, v62
	v_rsq_f32_e32 v62, v63
	s_nop 0
	v_mul_f32_e32 v30, v30, v62
	global_store_dword v31, v30, s[0:1] offset:16
.LBB0_304:
	s_or_b64 exec, exec, s[6:7]
	v_max_f32_e32 v24, v24, v24
	v_max_f32_e32 v25, v25, v25
	v_max_f32_e32 v24, v24, v25
	v_div_scale_f32 v25, s[6:7], v24, v24, s9
	v_rcp_f32_e32 v30, v25
	s_nop 0
	v_fma_f32 v31, -v25, v30, 1.0
	v_fmac_f32_e32 v30, v31, v30
	v_div_scale_f32 v31, vcc, s9, v24, s9
	v_mul_f32_e32 v62, v31, v30
	v_fma_f32 v63, -v25, v62, v31
	v_fmac_f32_e32 v62, v63, v30
	v_fma_f32 v25, -v25, v62, v31
	v_div_fmas_f32 v25, v25, v30, v62
	v_div_fixup_f32 v25, v25, v24, s9
	v_cmp_lt_f32_e32 vcc, 0, v24
	s_nop 1
	v_cndmask_b32_e32 v25, 0, v25, vcc
	v_mul_f32_e32 v31, v25, v59
	v_mul_f32_e32 v30, v25, v61
	v_rndne_f32_e32 v31, v31
	v_mul_f32_e32 v58, v25, v58
	v_mul_f32_e32 v57, v25, v57
	v_mul_f32_e32 v55, v25, v55
	v_rndne_f32_e32 v30, v30
	v_cvt_i32_f32_e32 v31, v31
	v_mul_f32_e32 v59, v25, v60
	v_rndne_f32_e32 v58, v58
	v_rndne_f32_e32 v57, v57
	v_mul_f32_e32 v56, v25, v56
	v_rndne_f32_e32 v55, v55
	v_mul_f32_e32 v54, v25, v54
	v_cvt_i32_f32_e32 v30, v30
	v_rndne_f32_e32 v59, v59
	v_cvt_i32_f32_e32 v58, v58
	v_cvt_i32_f32_sdwa v57, v57 dst_sel:WORD_1 dst_unused:UNUSED_PAD src0_sel:DWORD
	v_rndne_f32_e32 v56, v56
	v_cvt_i32_f32_e32 v55, v55
	v_rndne_f32_e32 v54, v54
	v_cvt_i32_f32_e32 v59, v59
	v_cvt_i32_f32_sdwa v56, v56 dst_sel:WORD_1 dst_unused:UNUSED_PAD src0_sel:DWORD
	v_cvt_i32_f32_e32 v54, v54
	v_lshlrev_b32_e32 v31, 8, v31
	v_and_b32_e32 v31, 0xff00, v31
	v_lshlrev_b32_e32 v58, 8, v58
	v_and_b32_e32 v57, 0xff0000, v57
	v_perm_b32 v30, v55, v30, s8
	v_and_b32_e32 v58, 0xff00, v58
	v_and_b32_e32 v56, 0xff0000, v56
	v_or3_b32 v30, v30, v31, v57
	v_perm_b32 v31, v54, v59, s8
	v_or3_b32 v31, v31, v58, v56
	v_mov_b32_e32 v204, v30
	v_mov_b32_e32 v205, v31
	v_mul_f32_e32 v31, v25, v51
	v_mul_f32_e32 v50, v25, v50
	v_mul_f32_e32 v30, v25, v53
	v_rndne_f32_e32 v31, v31
	v_mul_f32_e32 v51, v25, v52
	v_rndne_f32_e32 v50, v50
	v_mul_f32_e32 v49, v25, v49
	v_mul_f32_e32 v48, v25, v48
	v_mul_f32_e32 v47, v25, v47
	v_mul_f32_e32 v25, v25, v46
	v_rndne_f32_e32 v30, v30
	v_cvt_i32_f32_e32 v31, v31
	v_rndne_f32_e32 v51, v51
	v_cvt_i32_f32_e32 v50, v50
	v_rndne_f32_e32 v49, v49
	v_rndne_f32_e32 v48, v48
	v_rndne_f32_e32 v47, v47
	v_rndne_f32_e32 v25, v25
	v_cvt_i32_f32_e32 v30, v30
	v_cvt_i32_f32_e32 v51, v51
	v_cvt_i32_f32_sdwa v49, v49 dst_sel:WORD_1 dst_unused:UNUSED_PAD src0_sel:DWORD
	v_cvt_i32_f32_sdwa v48, v48 dst_sel:WORD_1 dst_unused:UNUSED_PAD src0_sel:DWORD
	v_cvt_i32_f32_e32 v47, v47
	v_cvt_i32_f32_e32 v25, v25
	v_lshlrev_b32_e32 v31, 8, v31
	v_lshlrev_b32_e32 v50, 8, v50
	v_and_b32_e32 v31, 0xff00, v31
	v_and_b32_e32 v50, 0xff00, v50
	v_and_b32_e32 v49, 0xff0000, v49
	v_and_b32_e32 v46, 0xff0000, v48
	v_perm_b32 v30, v47, v30, s8
	v_perm_b32 v25, v25, v51, s8
	v_or3_b32 v30, v30, v31, v49
	v_or3_b32 v31, v25, v50, v46
	v_mov_b32_e32 v206, v30
	v_mov_b32_e32 v207, v31
	global_store_dwordx4 v[4:5], v[204:207], off offset:1024
	s_and_saveexec_b64 s[6:7], s[4:5]
	s_cbranch_execz .LBB0_306
	v_mov_b32_e32 v25, 0
	v_mov_b32_e32 v46, v180
	v_mov_b32_e32 v47, v181
	v_mov_b32_e32 v48, v182
	v_mov_b32_e32 v49, v183
	v_mov_b32_e32 v4, v47
	v_mov_b32_e32 v5, v48
	v_mov_b32_e32 v47, v49
	v_pk_add_f32 v[4:5], v[4:5], v[46:47]
	s_nop 0
	v_add_f32_e32 v4, v4, v5
	v_mov_b32_e32 v5, 0x358637bd
	v_fmac_f32_e32 v5, 0x3a800000, v4
	v_rsq_f32_e32 v4, v5
	v_mul_f32_e32 v5, 0x3c010204, v24
	v_mul_f32_e32 v4, v5, v4
	global_store_dword v25, v4, s[0:1] offset:20
.LBB0_306:
	s_or_b64 exec, exec, s[6:7]
	v_max_f32_e32 v4, v20, v20
	v_max_f32_e32 v5, v21, v21
	v_max_f32_e32 v4, v4, v5
	v_div_scale_f32 v5, s[6:7], v4, v4, s9
	v_rcp_f32_e32 v20, v5
	s_movk_i32 s6, 0x1000
	v_fma_f32 v21, -v5, v20, 1.0
	v_fmac_f32_e32 v20, v21, v20
	v_div_scale_f32 v21, vcc, s9, v4, s9
	v_mul_f32_e32 v24, v21, v20
	v_fma_f32 v25, -v5, v24, v21
	v_fmac_f32_e32 v24, v25, v20
	v_fma_f32 v5, -v5, v24, v21
	v_div_fmas_f32 v5, v5, v20, v24
	v_div_fixup_f32 v5, v5, v4, s9
	v_cmp_lt_f32_e32 vcc, 0, v4
	s_nop 1
	v_cndmask_b32_e32 v5, 0, v5, vcc
	v_mul_f32_e32 v21, v5, v43
	v_mul_f32_e32 v20, v5, v45
	v_rndne_f32_e32 v21, v21
	v_mul_f32_e32 v25, v5, v42
	v_mul_f32_e32 v30, v5, v40
	v_mul_f32_e32 v39, v5, v39
	v_rndne_f32_e32 v20, v20
	v_cvt_i32_f32_e32 v21, v21
	v_mul_f32_e32 v24, v5, v44
	v_rndne_f32_e32 v25, v25
	v_rndne_f32_e32 v30, v30
	v_mul_f32_e32 v31, v5, v41
	v_rndne_f32_e32 v39, v39
	v_mul_f32_e32 v38, v5, v38
	v_cvt_i32_f32_e32 v20, v20
	v_rndne_f32_e32 v24, v24
	v_cvt_i32_f32_e32 v25, v25
	v_cvt_i32_f32_sdwa v30, v30 dst_sel:WORD_1 dst_unused:UNUSED_PAD src0_sel:DWORD
	v_rndne_f32_e32 v31, v31
	v_cvt_i32_f32_e32 v39, v39
	v_rndne_f32_e32 v38, v38
	v_cvt_i32_f32_e32 v24, v24
	v_cvt_i32_f32_sdwa v31, v31 dst_sel:WORD_1 dst_unused:UNUSED_PAD src0_sel:DWORD
	v_cvt_i32_f32_e32 v38, v38
	v_lshlrev_b32_e32 v21, 8, v21
	v_and_b32_e32 v21, 0xff00, v21
	v_lshlrev_b32_e32 v25, 8, v25
	v_and_b32_e32 v30, 0xff0000, v30
	v_perm_b32 v20, v39, v20, s8
	v_and_b32_e32 v25, 0xff00, v25
	v_and_b32_e32 v31, 0xff0000, v31
	v_or3_b32 v20, v20, v21, v30
	v_perm_b32 v21, v38, v24, s8
	v_add_co_u32_e32 v2, vcc, s6, v2
	v_or3_b32 v21, v21, v25, v31
	s_nop 0
	v_addc_co_u32_e32 v3, vcc, 0, v3, vcc
	v_mov_b32_e32 v200, v20
	v_mov_b32_e32 v201, v21
	v_mul_f32_e32 v21, v5, v35
	v_mul_f32_e32 v25, v5, v34
	v_mul_f32_e32 v20, v5, v37
	v_rndne_f32_e32 v21, v21
	v_mul_f32_e32 v24, v5, v36
	v_rndne_f32_e32 v25, v25
	v_mul_f32_e32 v30, v5, v33
	v_mul_f32_e32 v31, v5, v32
	v_mul_f32_e32 v29, v5, v29
	v_mul_f32_e32 v5, v5, v28
	v_rndne_f32_e32 v20, v20
	v_cvt_i32_f32_e32 v21, v21
	v_rndne_f32_e32 v24, v24
	v_cvt_i32_f32_e32 v25, v25
	v_rndne_f32_e32 v30, v30
	v_rndne_f32_e32 v31, v31
	v_rndne_f32_e32 v29, v29
	v_rndne_f32_e32 v5, v5
	v_cvt_i32_f32_e32 v20, v20
	v_cvt_i32_f32_e32 v24, v24
	v_cvt_i32_f32_sdwa v30, v30 dst_sel:WORD_1 dst_unused:UNUSED_PAD src0_sel:DWORD
	v_cvt_i32_f32_sdwa v31, v31 dst_sel:WORD_1 dst_unused:UNUSED_PAD src0_sel:DWORD
	v_cvt_i32_f32_e32 v29, v29
	v_cvt_i32_f32_e32 v5, v5
	v_lshlrev_b32_e32 v21, 8, v21
	v_lshlrev_b32_e32 v25, 8, v25
	v_and_b32_e32 v21, 0xff00, v21
	v_and_b32_e32 v25, 0xff00, v25
	v_and_b32_e32 v30, 0xff0000, v30
	v_and_b32_e32 v28, 0xff0000, v31
	v_perm_b32 v20, v29, v20, s8
	v_perm_b32 v5, v5, v24, s8
	v_or3_b32 v20, v20, v21, v30
	v_or3_b32 v21, v5, v25, v28
	v_mov_b32_e32 v202, v20
	v_mov_b32_e32 v203, v21
	global_store_dwordx4 v[2:3], v[200:203], off offset:2048
	s_and_saveexec_b64 s[6:7], s[4:5]
	s_cbranch_execz .LBB0_308
	v_mov_b32_e32 v5, 0
	v_mov_b32_e32 v28, v184
	v_mov_b32_e32 v29, v185
	v_mov_b32_e32 v30, v186
	v_mov_b32_e32 v31, v187
	v_mul_f32_e32 v4, 0x3c010204, v4
	v_mov_b32_e32 v20, v29
	v_mov_b32_e32 v21, v30
	v_mov_b32_e32 v29, v31
	v_pk_add_f32 v[20:21], v[20:21], v[28:29]
	s_nop 0
	v_add_f32_e32 v20, v20, v21
	v_mov_b32_e32 v21, 0x358637bd
	v_fmac_f32_e32 v21, 0x3a800000, v20
	v_rsq_f32_e32 v20, v21
	s_nop 0
	v_mul_f32_e32 v4, v4, v20
	global_store_dword v5, v4, s[0:1] offset:24
.LBB0_308:
	s_or_b64 exec, exec, s[6:7]
	v_max_f32_e32 v4, v18, v18
	v_max_f32_e32 v5, v19, v19
	v_max_f32_e32 v4, v4, v5
	v_div_scale_f32 v5, s[6:7], v4, v4, s9
	v_rcp_f32_e32 v18, v5
	s_nop 0
	v_fma_f32 v19, -v5, v18, 1.0
	v_fmac_f32_e32 v18, v19, v18
	v_div_scale_f32 v19, vcc, s9, v4, s9
	v_mul_f32_e32 v20, v19, v18
	v_fma_f32 v21, -v5, v20, v19
	v_fmac_f32_e32 v20, v21, v18
	v_fma_f32 v5, -v5, v20, v19
	v_div_fmas_f32 v5, v5, v18, v20
	v_div_fixup_f32 v5, v5, v4, s9
	v_cmp_lt_f32_e32 vcc, 0, v4
	s_nop 1
	v_cndmask_b32_e32 v5, 0, v5, vcc
	v_mul_f32_e32 v19, v5, v26
	v_mul_f32_e32 v21, v5, v22
	v_mul_f32_e32 v11, v5, v11
	v_mul_f32_e32 v10, v5, v10
	v_mul_f32_e32 v18, v5, v27
	v_rndne_f32_e32 v19, v19
	v_mul_f32_e32 v20, v5, v23
	v_rndne_f32_e32 v21, v21
	v_mul_f32_e32 v17, v5, v17
	v_mul_f32_e32 v16, v5, v16
	v_mul_f32_e32 v15, v5, v15
	v_mul_f32_e32 v14, v5, v14
	v_mul_f32_e32 v13, v5, v13
	v_rndne_f32_e32 v11, v11
	v_mul_f32_e32 v12, v5, v12
	v_rndne_f32_e32 v10, v10
	v_mul_f32_e32 v9, v5, v9
	v_mul_f32_e32 v8, v5, v8
	v_mul_f32_e32 v7, v5, v7
	v_mul_f32_e32 v5, v5, v6
	v_rndne_f32_e32 v18, v18
	v_cvt_i32_f32_e32 v19, v19
	v_rndne_f32_e32 v20, v20
	v_cvt_i32_f32_e32 v21, v21
	v_rndne_f32_e32 v17, v17
	v_rndne_f32_e32 v16, v16
	v_rndne_f32_e32 v15, v15
	v_rndne_f32_e32 v14, v14
	v_rndne_f32_e32 v13, v13
	v_cvt_i32_f32_e32 v11, v11
	v_rndne_f32_e32 v12, v12
	v_cvt_i32_f32_e32 v10, v10
	v_rndne_f32_e32 v9, v9
	v_rndne_f32_e32 v8, v8
	v_rndne_f32_e32 v7, v7
	v_rndne_f32_e32 v5, v5
	v_cvt_i32_f32_e32 v18, v18
	v_cvt_i32_f32_e32 v20, v20
	v_cvt_i32_f32_sdwa v17, v17 dst_sel:WORD_1 dst_unused:UNUSED_PAD src0_sel:DWORD
	v_cvt_i32_f32_sdwa v16, v16 dst_sel:WORD_1 dst_unused:UNUSED_PAD src0_sel:DWORD
	v_cvt_i32_f32_e32 v15, v15
	v_cvt_i32_f32_e32 v22, v14
	v_cvt_i32_f32_e32 v13, v13
	v_cvt_i32_f32_e32 v12, v12
	v_cvt_i32_f32_sdwa v9, v9 dst_sel:WORD_1 dst_unused:UNUSED_PAD src0_sel:DWORD
	v_cvt_i32_f32_sdwa v8, v8 dst_sel:WORD_1 dst_unused:UNUSED_PAD src0_sel:DWORD
	v_cvt_i32_f32_e32 v7, v7
	v_cvt_i32_f32_e32 v5, v5
	v_lshlrev_b32_e32 v19, 8, v19
	v_lshlrev_b32_e32 v21, 8, v21
	v_lshlrev_b32_e32 v11, 8, v11
	v_lshlrev_b32_e32 v10, 8, v10
	v_and_b32_e32 v19, 0xff00, v19
	v_and_b32_e32 v21, 0xff00, v21
	v_and_b32_e32 v17, 0xff0000, v17
	v_and_b32_e32 v16, 0xff0000, v16
	v_perm_b32 v14, v15, v18, s8
	v_perm_b32 v15, v22, v20, s8
	v_and_b32_e32 v11, 0xff00, v11
	v_and_b32_e32 v10, 0xff00, v10
	v_and_b32_e32 v9, 0xff0000, v9
	v_and_b32_e32 v8, 0xff0000, v8
	v_perm_b32 v6, v7, v13, s8
	v_perm_b32 v5, v5, v12, s8
	v_or3_b32 v14, v14, v19, v17
	v_or3_b32 v15, v15, v21, v16
	v_or3_b32 v6, v6, v11, v9
	v_or3_b32 v7, v5, v10, v8
	v_mov_b32_e32 v204, v14
	v_mov_b32_e32 v205, v15
	v_mov_b32_e32 v206, v6
	v_mov_b32_e32 v207, v7
	global_store_dwordx4 v[2:3], v[204:207], off offset:3072
	s_and_saveexec_b64 s[6:7], s[4:5]
	s_cbranch_execz .LBB0_310
	v_mov_b32_e32 v5, 0
	v_mov_b32_e32 v6, v188
	v_mov_b32_e32 v7, v189
	v_mov_b32_e32 v8, v190
	v_mov_b32_e32 v9, v191
	v_mov_b32_e32 v2, v7
	v_mov_b32_e32 v3, v8
	v_mov_b32_e32 v7, v9
	v_pk_add_f32 v[2:3], v[2:3], v[6:7]
	s_nop 0
	v_add_f32_e32 v2, v2, v3
	v_mov_b32_e32 v3, 0x358637bd
	v_fmac_f32_e32 v3, 0x3a800000, v2
	v_rsq_f32_e32 v2, v3
	v_mul_f32_e32 v3, 0x3c010204, v4
	v_mul_f32_e32 v2, v3, v2
	global_store_dword v5, v2, s[0:1] offset:28

.LBB0_542:
	s_or_b64 exec, exec, s[0:1]
	s_mov_b64 s[0:1], s[82:83]
	v_mov_b32_e32 v2, v0
	s_mov_b32 s5, s72
	s_mov_b32 s2, s73
	s_barrier
	s_load_dwordx2 s[2:3], s[0:1], 0x90
	v_readfirstlane_b32 s4, v2
	s_lshl_b32 s0, s5, 3
	s_and_b32 s0, s0, 56
	s_bfe_u32 s1, s5, 0x30003
	s_ashr_i32 s4, s4, 3
	s_or_b32 s8, s0, s1
	s_and_b32 s1, s5, 0xffffffc0
	s_and_b32 s4, s4, -8
	s_lshl_b32 s0, s8, 8
	s_add_i32 s4, s1, s4
	s_add_i32 s6, s4, s0
	s_ashr_i32 s7, s6, 31
	s_lshl_b64 s[0:1], s[6:7], 11
	v_and_b32_e32 v126, 63, v2
	s_waitcnt lgkmcnt(0)
	s_add_u32 s0, s2, s0
	s_addc_u32 s1, s3, s1
	v_lshlrev_b32_e32 v30, 5, v126
	v_mov_b32_e32 v31, 0
	v_lshl_add_u64 v[2:3], s[0:1], 0, v[30:31]
	s_mov_b32 s0, 0x3001000
	v_add_co_u32_e32 v60, vcc, s0, v2
	s_mov_b64 s[0:1], 0x3000000
	s_nop 0
	v_addc_co_u32_e32 v61, vcc, 0, v3, vcc
	global_load_dwordx4 v[18:21], v[60:61], off offset:-4096
	v_lshl_add_u64 v[4:5], v[2:3], 0, s[0:1]
	global_load_dwordx4 v[22:25], v[4:5], off offset:16
	global_load_dwordx4 v[32:35], v[4:5], off offset:2048
	global_load_dwordx4 v[36:39], v[4:5], off offset:2064
	s_mov_b32 s0, 0x3002000
	v_add_co_u32_e32 v62, vcc, s0, v2
	s_mov_b32 s1, 0x3003000
	s_nop 0
	v_addc_co_u32_e32 v63, vcc, 0, v3, vcc
	v_add_co_u32_e32 v64, vcc, s1, v2
	s_mul_i32 s8, s8, 0x160000
	s_nop 0
	v_addc_co_u32_e32 v65, vcc, 0, v3, vcc
	global_load_dwordx4 v[40:43], v[60:61], off
	global_load_dwordx4 v[44:47], v[60:61], off offset:16
	global_load_dwordx4 v[48:51], v[60:61], off offset:2048
	global_load_dwordx4 v[52:55], v[60:61], off offset:2064
	global_load_dwordx4 v[56:59], v[64:65], off offset:-4096
	global_load_dwordx4 v[26:29], v[62:63], off offset:16
	global_load_dwordx4 v[14:17], v[62:63], off offset:2048
	global_load_dwordx4 v[10:13], v[62:63], off offset:2064
	global_load_dwordx4 v[6:9], v[64:65], off
	global_load_dwordx4 v[2:5], v[64:65], off offset:16
	s_add_u32 s5, s2, s8
	s_addc_u32 s8, s3, 0
	s_lshl_b32 s4, s4, 10
	s_and_b32 s0, s4, 0x3e000
	s_add_u32 s4, s5, s0
	s_addc_u32 s5, s8, 0
	s_mov_b32 s9, 0x42fe0000
	s_lshl_b64 s[0:1], s[6:7], 2
	s_add_u32 s0, s2, s0
	s_addc_u32 s1, s3, s1
	s_add_u32 s0, s0, 0xfc00000
	s_addc_u32 s1, s1, 0
	s_lshl_b64 s[6:7], s[6:7], 4
	s_mov_b32 s8, 0x40c0c00
	s_add_u32 s2, s2, s6
	s_mov_b32 s6, 0x5000000
	s_addc_u32 s3, s3, s7
	s_add_u32 s2, s2, 0xda00000
	s_addc_u32 s3, s3, 0
	v_mov_b32_e32 v192, 0
	global_load_dwordx4 v[160:163], v192, s[2:3]
	global_load_dwordx4 v[164:167], v192, s[2:3] offset:16
	global_load_dwordx4 v[168:171], v192, s[2:3] offset:32
	global_load_dwordx4 v[172:175], v192, s[2:3] offset:48
	global_load_dwordx4 v[176:179], v192, s[2:3] offset:64
	global_load_dwordx4 v[180:183], v192, s[2:3] offset:80
	global_load_dwordx4 v[184:187], v192, s[2:3] offset:96
	global_load_dwordx4 v[188:191], v192, s[2:3] offset:112
	s_waitcnt vmcnt(12)
	v_lshlrev_b32_e32 v148, 16, v22
	v_lshlrev_b32_e32 v140, 16, v18
	v_and_b32_e32 v141, 0xffff0000, v18
	v_lshlrev_b32_e32 v142, 16, v19
	v_and_b32_e32 v143, 0xffff0000, v19
	v_max3_f32 v18, |v140|, 0, |v141|
	v_lshlrev_b32_e32 v144, 16, v20
	v_and_b32_e32 v145, 0xffff0000, v20
	v_max3_f32 v18, v18, |v142|, |v143|
	v_lshlrev_b32_e32 v146, 16, v21
	v_and_b32_e32 v147, 0xffff0000, v21
	v_max3_f32 v18, v18, |v144|, |v145|
	v_and_b32_e32 v149, 0xffff0000, v22
	v_max3_f32 v18, v18, |v146|, |v147|
	v_lshlrev_b32_e32 v134, 16, v23
	v_and_b32_e32 v132, 0xffff0000, v23
	v_max3_f32 v18, v18, |v148|, |v149|
	v_lshlrev_b32_e32 v150, 16, v24
	v_and_b32_e32 v151, 0xffff0000, v24
	v_max3_f32 v18, v18, |v134|, |v132|
	v_lshlrev_b32_e32 v133, 16, v25
	v_and_b32_e32 v131, 0xffff0000, v25
	v_max3_f32 v18, v18, |v150|, |v151|
	v_max3_f32 v18, v18, |v133|, |v131|
	ds_swizzle_b32 v19, v18 offset:swizzle(SWAP,1)
	s_waitcnt vmcnt(11)
	v_lshlrev_b32_e32 v130, 16, v32
	v_and_b32_e32 v128, 0xffff0000, v32
	v_lshlrev_b32_e32 v122, 16, v33
	v_and_b32_e32 v119, 0xffff0000, v33
	s_waitcnt lgkmcnt(0)
	v_max_f32_e32 v19, v19, v19
	v_max_f32_e32 v18, v18, v19
	ds_swizzle_b32 v19, v18 offset:swizzle(SWAP,2)
	v_max3_f32 v20, |v130|, 0, |v128|
	v_lshlrev_b32_e32 v129, 16, v34
	v_and_b32_e32 v127, 0xffff0000, v34
	v_max3_f32 v20, v20, |v122|, |v119|
	s_waitcnt lgkmcnt(0)
	v_max_f32_e32 v19, v19, v19
	v_max_f32_e32 v18, v18, v19
	ds_swizzle_b32 v19, v18 offset:swizzle(SWAP,4)
	v_lshlrev_b32_e32 v123, 16, v35
	v_and_b32_e32 v121, 0xffff0000, v35
	v_max3_f32 v20, v20, |v129|, |v127|
	s_waitcnt vmcnt(10)
	v_lshlrev_b32_e32 v117, 16, v36
	s_waitcnt lgkmcnt(0)
	v_max_f32_e32 v19, v19, v19
	v_max_f32_e32 v18, v18, v19
	ds_swizzle_b32 v19, v18 offset:swizzle(SWAP,8)
	v_and_b32_e32 v116, 0xffff0000, v36
	v_max3_f32 v20, v20, |v123|, |v121|
	v_lshlrev_b32_e32 v113, 16, v37
	v_and_b32_e32 v114, 0xffff0000, v37
	s_waitcnt lgkmcnt(0)
	v_max_f32_e32 v19, v19, v19
	v_max_f32_e32 v30, v18, v19
	v_max3_f32 v18, v20, |v117|, |v116|
	v_lshlrev_b32_e32 v120, 16, v38
	v_and_b32_e32 v118, 0xffff0000, v38
	v_max3_f32 v18, v18, |v113|, |v114|
	v_lshlrev_b32_e32 v115, 16, v39
	v_and_b32_e32 v112, 0xffff0000, v39
	v_max3_f32 v18, v18, |v120|, |v118|
	ds_swizzle_b32 v32, v30 offset:swizzle(SWAP,16)
	v_max3_f32 v33, v18, |v115|, |v112|
	ds_swizzle_b32 v34, v33 offset:swizzle(SWAP,1)
	s_waitcnt vmcnt(9)
	v_lshlrev_b32_e32 v111, 16, v40
	v_and_b32_e32 v109, 0xffff0000, v40
	s_waitcnt lgkmcnt(1)
	v_max_f32_e32 v32, v32, v32
	v_max_f32_e32 v30, v30, v32
	s_waitcnt lgkmcnt(0)
	v_max_f32_e32 v32, v34, v34
	v_max_f32_e32 v32, v33, v32
	v_lshlrev_b32_e32 v106, 16, v41
	v_and_b32_e32 v105, 0xffff0000, v41
	v_max3_f32 v35, |v111|, 0, |v109|
	global_load_dwordx4 v[22:25], v[64:65], off offset:2048
	global_load_dwordx4 v[18:21], v[64:65], off offset:2064
	ds_swizzle_b32 v33, v32 offset:swizzle(SWAP,2)
	v_lshlrev_b32_e32 v110, 16, v42
	v_and_b32_e32 v108, 0xffff0000, v42
	v_max3_f32 v35, v35, |v106|, |v105|
	v_lshlrev_b32_e32 v107, 16, v43
	v_and_b32_e32 v104, 0xffff0000, v43
	v_max3_f32 v35, v35, |v110|, |v108|
	v_max3_f32 v35, v35, |v107|, |v104|
	s_waitcnt vmcnt(10)
	v_lshlrev_b32_e32 v103, 16, v44
	v_and_b32_e32 v101, 0xffff0000, v44
	v_lshlrev_b32_e32 v99, 16, v45
	v_and_b32_e32 v95, 0xffff0000, v45
	v_max3_f32 v35, v35, |v103|, |v101|
	v_lshlrev_b32_e32 v102, 16, v46
	v_and_b32_e32 v100, 0xffff0000, v46
	v_max3_f32 v35, v35, |v99|, |v95|
	s_waitcnt lgkmcnt(0)
	v_max_f32_e32 v33, v33, v33
	v_lshlrev_b32_e32 v98, 16, v47
	v_and_b32_e32 v94, 0xffff0000, v47
	v_max3_f32 v35, v35, |v102|, |v100|
	v_max_f32_e32 v32, v32, v33
	v_max3_f32 v35, v35, |v98|, |v94|
	ds_swizzle_b32 v33, v32 offset:swizzle(SWAP,4)
	ds_swizzle_b32 v36, v35 offset:swizzle(SWAP,1)
	v_mov_b32_e32 v34, v30
	s_nop 1
	v_permlane32_swap_b32_e32 v30, v34
	s_waitcnt lgkmcnt(1)
	v_max_f32_e32 v33, v33, v33
	s_waitcnt lgkmcnt(0)
	v_max_f32_e32 v36, v36, v36
	v_max_f32_e32 v32, v32, v33
	v_max_f32_e32 v35, v35, v36
	ds_swizzle_b32 v33, v32 offset:swizzle(SWAP,8)
	ds_swizzle_b32 v36, v35 offset:swizzle(SWAP,2)
	v_max_f32_e32 v34, v34, v34
	v_max_f32_e32 v30, v30, v30
	v_max_f32_e32 v137, v30, v34
	s_waitcnt lgkmcnt(1)
	v_max_f32_e32 v30, v33, v33
	s_waitcnt lgkmcnt(0)
	v_max_f32_e32 v33, v36, v36
	s_waitcnt vmcnt(9)
	v_lshlrev_b32_e32 v93, 16, v48
	v_and_b32_e32 v91, 0xffff0000, v48
	v_max_f32_e32 v33, v35, v33
	v_lshlrev_b32_e32 v89, 16, v49
	v_and_b32_e32 v87, 0xffff0000, v49
	v_max3_f32 v35, |v93|, 0, |v91|
	v_lshlrev_b32_e32 v92, 16, v50
	v_and_b32_e32 v90, 0xffff0000, v50
	v_max3_f32 v35, v35, |v89|, |v87|
	v_lshlrev_b32_e32 v88, 16, v51
	v_and_b32_e32 v86, 0xffff0000, v51
	v_max3_f32 v35, v35, |v92|, |v90|
	v_max3_f32 v35, v35, |v88|, |v86|
	s_waitcnt vmcnt(8)
	v_lshlrev_b32_e32 v85, 16, v52
	v_and_b32_e32 v83, 0xffff0000, v52
	v_lshlrev_b32_e32 v81, 16, v53
	v_and_b32_e32 v79, 0xffff0000, v53
	v_max3_f32 v35, v35, |v85|, |v83|
	v_lshlrev_b32_e32 v84, 16, v54
	v_and_b32_e32 v82, 0xffff0000, v54
	v_max3_f32 v35, v35, |v81|, |v79|
	v_lshlrev_b32_e32 v80, 16, v55
	v_and_b32_e32 v78, 0xffff0000, v55
	v_max3_f32 v35, v35, |v84|, |v82|
	ds_swizzle_b32 v34, v33 offset:swizzle(SWAP,4)
	v_max3_f32 v35, v35, |v80|, |v78|
	ds_swizzle_b32 v36, v35 offset:swizzle(SWAP,1)
	v_max_f32_e32 v30, v32, v30
	ds_swizzle_b32 v32, v30 offset:swizzle(SWAP,16)
	s_waitcnt lgkmcnt(2)
	v_max_f32_e32 v34, v34, v34
	v_max_f32_e32 v33, v33, v34
	s_waitcnt lgkmcnt(1)
	v_max_f32_e32 v36, v36, v36
	ds_swizzle_b32 v34, v33 offset:swizzle(SWAP,8)
	v_max_f32_e32 v35, v35, v36
	ds_swizzle_b32 v36, v35 offset:swizzle(SWAP,2)
	s_waitcnt lgkmcnt(2)
	v_max_f32_e32 v32, v32, v32
	v_max_f32_e32 v138, v30, v32
	s_waitcnt lgkmcnt(1)
	v_max_f32_e32 v30, v34, v34
	v_max_f32_e32 v30, v33, v30
	s_waitcnt lgkmcnt(0)
	v_max_f32_e32 v33, v36, v36
	s_waitcnt vmcnt(7)
	v_lshlrev_b32_e32 v77, 16, v56
	v_and_b32_e32 v75, 0xffff0000, v56
	v_max_f32_e32 v33, v35, v33
	v_lshlrev_b32_e32 v72, 16, v57
	v_and_b32_e32 v71, 0xffff0000, v57
	v_max3_f32 v35, |v77|, 0, |v75|
	v_lshlrev_b32_e32 v76, 16, v58
	v_and_b32_e32 v74, 0xffff0000, v58
	v_max3_f32 v35, v35, |v72|, |v71|
	v_lshlrev_b32_e32 v73, 16, v59
	v_and_b32_e32 v70, 0xffff0000, v59
	v_max3_f32 v35, v35, |v76|, |v74|
	v_max3_f32 v35, v35, |v73|, |v70|
	s_waitcnt vmcnt(6)
	v_lshlrev_b32_e32 v69, 16, v26
	v_and_b32_e32 v67, 0xffff0000, v26
	v_lshlrev_b32_e32 v65, 16, v27
	v_and_b32_e32 v63, 0xffff0000, v27
	v_max3_f32 v26, v35, |v69|, |v67|
	v_lshlrev_b32_e32 v68, 16, v28
	v_and_b32_e32 v66, 0xffff0000, v28
	v_max3_f32 v26, v26, |v65|, |v63|
	v_lshlrev_b32_e32 v64, 16, v29
	v_and_b32_e32 v62, 0xffff0000, v29
	v_max3_f32 v26, v26, |v68|, |v66|
	v_max3_f32 v26, v26, |v64|, |v62|
	s_waitcnt vmcnt(5)
	v_lshlrev_b32_e32 v61, 16, v14
	v_and_b32_e32 v59, 0xffff0000, v14
	ds_swizzle_b32 v27, v26 offset:swizzle(SWAP,1)
	v_lshlrev_b32_e32 v57, 16, v15
	v_and_b32_e32 v55, 0xffff0000, v15
	v_max3_f32 v14, |v61|, 0, |v59|
	v_lshlrev_b32_e32 v60, 16, v16
	v_and_b32_e32 v58, 0xffff0000, v16
	v_max3_f32 v14, v14, |v57|, |v55|
	v_lshlrev_b32_e32 v56, 16, v17
	v_and_b32_e32 v54, 0xffff0000, v17
	v_max3_f32 v14, v14, |v60|, |v58|
	v_max3_f32 v14, v14, |v56|, |v54|
	s_waitcnt vmcnt(4)
	v_lshlrev_b32_e32 v53, 16, v10
	v_and_b32_e32 v51, 0xffff0000, v10
	v_lshlrev_b32_e32 v49, 16, v11
	v_and_b32_e32 v47, 0xffff0000, v11
	v_max3_f32 v10, v14, |v53|, |v51|
	s_waitcnt lgkmcnt(0)
	v_max_f32_e32 v27, v27, v27
	v_lshlrev_b32_e32 v52, 16, v12
	v_and_b32_e32 v50, 0xffff0000, v12
	v_max3_f32 v10, v10, |v49|, |v47|
	v_max_f32_e32 v26, v26, v27
	v_lshlrev_b32_e32 v48, 16, v13
	v_and_b32_e32 v46, 0xffff0000, v13
	v_max3_f32 v10, v10, |v52|, |v50|
	ds_swizzle_b32 v27, v26 offset:swizzle(SWAP,2)
	v_max3_f32 v10, v10, |v48|, |v46|
	ds_swizzle_b32 v11, v10 offset:swizzle(SWAP,1)
	ds_swizzle_b32 v34, v33 offset:swizzle(SWAP,4)
	ds_swizzle_b32 v32, v30 offset:swizzle(SWAP,16)
	s_waitcnt lgkmcnt(3)
	v_max_f32_e32 v27, v27, v27
	v_max_f32_e32 v26, v26, v27
	s_waitcnt lgkmcnt(2)
	v_max_f32_e32 v11, v11, v11
	ds_swizzle_b32 v27, v26 offset:swizzle(SWAP,4)
	v_max_f32_e32 v10, v10, v11
	ds_swizzle_b32 v11, v10 offset:swizzle(SWAP,2)
	s_waitcnt lgkmcnt(3)
	v_max_f32_e32 v34, v34, v34
	v_max_f32_e32 v33, v33, v34
	ds_swizzle_b32 v34, v33 offset:swizzle(SWAP,8)
	s_waitcnt lgkmcnt(2)
	v_max_f32_e32 v12, v27, v27
	v_max_f32_e32 v12, v26, v12
	s_waitcnt lgkmcnt(1)
	v_max_f32_e32 v11, v11, v11
	ds_swizzle_b32 v13, v12 offset:swizzle(SWAP,8)
	v_max_f32_e32 v10, v10, v11
	ds_swizzle_b32 v11, v10 offset:swizzle(SWAP,4)
	s_waitcnt lgkmcnt(2)
	v_max_f32_e32 v28, v34, v34
	v_max_f32_e32 v28, v33, v28
	ds_swizzle_b32 v29, v28 offset:swizzle(SWAP,16)
	s_waitcnt lgkmcnt(2)
	v_max_f32_e32 v13, v13, v13
	v_max_f32_e32 v12, v12, v13
	s_waitcnt lgkmcnt(1)
	v_max_f32_e32 v11, v11, v11
	ds_swizzle_b32 v13, v12 offset:swizzle(SWAP,16)
	v_max_f32_e32 v10, v10, v11
	ds_swizzle_b32 v11, v10 offset:swizzle(SWAP,8)
	s_waitcnt vmcnt(3)
	v_lshlrev_b32_e32 v45, 16, v6
	v_and_b32_e32 v43, 0xffff0000, v6
	v_max_f32_e32 v32, v32, v32
	s_waitcnt lgkmcnt(2)
	v_max_f32_e32 v29, v29, v29
	v_lshlrev_b32_e32 v40, 16, v7
	v_and_b32_e32 v39, 0xffff0000, v7
	v_max3_f32 v6, |v45|, 0, |v43|
	s_waitcnt vmcnt(1)
	v_lshlrev_b32_e32 v27, 16, v22
	v_and_b32_e32 v26, 0xffff0000, v22
	v_max_f32_e32 v135, v30, v32
	v_max_f32_e32 v124, v28, v29
	v_lshlrev_b32_e32 v44, 16, v8
	v_and_b32_e32 v42, 0xffff0000, v8
	v_max3_f32 v6, v6, |v40|, |v39|
	v_lshlrev_b32_e32 v32, 16, v5
	v_and_b32_e32 v28, 0xffff0000, v5
	v_lshlrev_b32_e32 v17, 16, v23
	v_and_b32_e32 v15, 0xffff0000, v23
	v_max3_f32 v5, |v27|, 0, |v26|
	v_lshlrev_b32_e32 v41, 16, v9
	v_and_b32_e32 v38, 0xffff0000, v9
	v_max3_f32 v6, v6, |v44|, |v42|
	v_lshlrev_b32_e32 v23, 16, v24
	v_and_b32_e32 v22, 0xffff0000, v24
	v_max3_f32 v5, v5, |v17|, |v15|
	s_waitcnt lgkmcnt(1)
	v_max_f32_e32 v13, v13, v13
	v_max3_f32 v6, v6, |v41|, |v38|
	v_lshlrev_b32_e32 v37, 16, v2
	v_and_b32_e32 v35, 0xffff0000, v2
	v_lshlrev_b32_e32 v16, 16, v25
	v_and_b32_e32 v14, 0xffff0000, v25
	v_max3_f32 v5, v5, |v23|, |v22|
	v_max_f32_e32 v96, v12, v13
	v_lshlrev_b32_e32 v33, 16, v3
	v_and_b32_e32 v29, 0xffff0000, v3
	v_lshlrev_b32_e32 v36, 16, v4
	v_and_b32_e32 v34, 0xffff0000, v4
	v_max3_f32 v2, v6, |v37|, |v35|
	s_waitcnt lgkmcnt(0)
	v_max_f32_e32 v4, v11, v11
	v_max3_f32 v5, v5, |v16|, |v14|
	s_waitcnt vmcnt(0)
	v_lshlrev_b32_e32 v13, 16, v18
	v_and_b32_e32 v11, 0xffff0000, v18
	v_max3_f32 v2, v2, |v33|, |v29|
	v_lshlrev_b32_e32 v9, 16, v19
	v_and_b32_e32 v7, 0xffff0000, v19
	v_max3_f32 v5, v5, |v13|, |v11|
	v_max3_f32 v2, v2, |v36|, |v34|
	v_max_f32_e32 v4, v10, v4
	v_lshlrev_b32_e32 v12, 16, v20
	v_and_b32_e32 v10, 0xffff0000, v20
	v_max3_f32 v5, v5, |v9|, |v7|
	v_max3_f32 v2, v2, |v32|, |v28|
	v_lshlrev_b32_e32 v8, 16, v21
	v_and_b32_e32 v6, 0xffff0000, v21
	v_max3_f32 v5, v5, |v12|, |v10|
	ds_swizzle_b32 v3, v2 offset:swizzle(SWAP,1)
	v_max3_f32 v5, v5, |v8|, |v6|
	ds_swizzle_b32 v18, v5 offset:swizzle(SWAP,1)
	ds_swizzle_b32 v19, v4 offset:swizzle(SWAP,16)
	v_lshlrev_b32_e32 v30, 4, v126
	s_waitcnt lgkmcnt(2)
	v_max_f32_e32 v3, v3, v3
	v_max_f32_e32 v2, v2, v3
	s_waitcnt lgkmcnt(1)
	v_max_f32_e32 v18, v18, v18
	ds_swizzle_b32 v3, v2 offset:swizzle(SWAP,2)
	v_max_f32_e32 v5, v5, v18
	ds_swizzle_b32 v18, v5 offset:swizzle(SWAP,2)
	s_waitcnt lgkmcnt(2)
	v_max_f32_e32 v19, v19, v19
	v_max_f32_e32 v24, v4, v19
	s_waitcnt lgkmcnt(1)
	v_max_f32_e32 v3, v3, v3
	v_max_f32_e32 v2, v2, v3
	s_waitcnt lgkmcnt(0)
	v_max_f32_e32 v18, v18, v18
	ds_swizzle_b32 v3, v2 offset:swizzle(SWAP,4)
	v_max_f32_e32 v5, v5, v18
	ds_swizzle_b32 v18, v5 offset:swizzle(SWAP,4)
	v_mov_b32_e32 v139, v138
	v_mov_b32_e32 v136, v135
	s_waitcnt lgkmcnt(1)
	v_max_f32_e32 v3, v3, v3
	v_max_f32_e32 v2, v2, v3
	s_waitcnt lgkmcnt(0)
	v_max_f32_e32 v4, v18, v18
	ds_swizzle_b32 v3, v2 offset:swizzle(SWAP,8)
	v_max_f32_e32 v4, v5, v4
	ds_swizzle_b32 v5, v4 offset:swizzle(SWAP,8)
	v_mov_b32_e32 v125, v124
	v_mov_b32_e32 v97, v96
	s_waitcnt lgkmcnt(1)
	v_max_f32_e32 v3, v3, v3
	v_max_f32_e32 v2, v2, v3
	s_waitcnt lgkmcnt(0)
	v_max_f32_e32 v5, v5, v5
	ds_swizzle_b32 v3, v2 offset:swizzle(SWAP,16)
	v_max_f32_e32 v4, v4, v5
	ds_swizzle_b32 v5, v4 offset:swizzle(SWAP,16)
	v_mov_b32_e32 v25, v24
	v_permlane32_swap_b32_e32 v138, v139
	s_waitcnt lgkmcnt(1)
	v_max_f32_e32 v3, v3, v3
	v_max_f32_e32 v20, v2, v3
	s_waitcnt lgkmcnt(0)
	v_max_f32_e32 v2, v5, v5
	v_max_f32_e32 v18, v4, v2
	v_lshl_add_u64 v[4:5], s[4:5], 0, v[30:31]
	v_div_scale_f32 v30, s[4:5], v137, v137, s9
	v_rcp_f32_e32 v152, v30
	s_mov_b64 s[4:5], 0x5000000
	v_lshl_add_u64 v[2:3], v[4:5], 0, s[4:5]
	v_cmp_eq_u32_e64 s[4:5], 0, v126
	v_fma_f32 v126, -v30, v152, 1.0
	v_fmac_f32_e32 v152, v126, v152
	v_div_scale_f32 v126, vcc, s9, v137, s9
	v_mul_f32_e32 v153, v126, v152
	v_fma_f32 v154, -v30, v153, v126
	v_fmac_f32_e32 v153, v154, v152
	v_fma_f32 v30, -v30, v153, v126
	v_div_fmas_f32 v30, v30, v152, v153
	v_div_fixup_f32 v30, v30, v137, s9
	v_cmp_lt_f32_e32 vcc, 0, v137
	v_mov_b32_e32 v21, v20
	v_mov_b32_e32 v19, v18
	v_cndmask_b32_e32 v30, 0, v30, vcc
	v_mul_f32_e32 v126, v30, v140
	v_mul_f32_e32 v140, v30, v141
	v_rndne_f32_e32 v140, v140
	v_mul_f32_e32 v141, v30, v144
	v_mul_f32_e32 v144, v30, v145
	v_mul_f32_e32 v142, v30, v142
	v_mul_f32_e32 v143, v30, v143
	v_rndne_f32_e32 v126, v126
	v_cvt_i32_f32_e32 v140, v140
	v_rndne_f32_e32 v144, v144
	v_rndne_f32_e32 v142, v142
	v_mul_f32_e32 v145, v30, v146
	v_rndne_f32_e32 v143, v143
	v_mul_f32_e32 v146, v30, v147
	v_cvt_i32_f32_e32 v126, v126
	v_rndne_f32_e32 v141, v141
	v_cvt_i32_f32_e32 v144, v144
	v_cvt_i32_f32_sdwa v142, v142 dst_sel:WORD_1 dst_unused:UNUSED_PAD src0_sel:DWORD
	v_rndne_f32_e32 v145, v145
	v_cvt_i32_f32_e32 v143, v143
	v_rndne_f32_e32 v146, v146
	v_cvt_i32_f32_e32 v141, v141
	v_cvt_i32_f32_sdwa v145, v145 dst_sel:WORD_1 dst_unused:UNUSED_PAD src0_sel:DWORD
	v_cvt_i32_f32_e32 v146, v146
	v_lshlrev_b32_e32 v140, 8, v140
	v_and_b32_e32 v140, 0xff00, v140
	v_lshlrev_b32_e32 v144, 8, v144
	v_and_b32_e32 v142, 0xff0000, v142
	v_perm_b32 v126, v143, v126, s8
	v_and_b32_e32 v144, 0xff00, v144
	v_and_b32_e32 v145, 0xff0000, v145
	v_or3_b32 v140, v126, v140, v142
	v_perm_b32 v126, v146, v141, s8
	v_add_co_u32_e32 v4, vcc, s6, v4
	v_or3_b32 v141, v126, v144, v145
	s_nop 0
	v_addc_co_u32_e32 v5, vcc, 0, v5, vcc
	v_mov_b32_e32 v200, v140
	v_mov_b32_e32 v201, v141
	v_mul_f32_e32 v5, v30, v149
	v_mul_f32_e32 v4, v30, v148
	v_rndne_f32_e32 v5, v5
	v_mul_f32_e32 v140, v30, v151
	v_mul_f32_e32 v134, v30, v134
	v_mul_f32_e32 v132, v30, v132
	v_rndne_f32_e32 v4, v4
	v_cvt_i32_f32_e32 v5, v5
	v_mul_f32_e32 v126, v30, v150
	v_rndne_f32_e32 v140, v140
	v_rndne_f32_e32 v134, v134
	v_mul_f32_e32 v133, v30, v133
	v_rndne_f32_e32 v132, v132
	v_mul_f32_e32 v30, v30, v131
	v_cvt_i32_f32_e32 v4, v4
	v_rndne_f32_e32 v126, v126
	v_cvt_i32_f32_e32 v140, v140
	v_cvt_i32_f32_sdwa v134, v134 dst_sel:WORD_1 dst_unused:UNUSED_PAD src0_sel:DWORD
	v_rndne_f32_e32 v133, v133
	v_cvt_i32_f32_e32 v132, v132
	v_rndne_f32_e32 v30, v30
	v_cvt_i32_f32_e32 v126, v126
	v_cvt_i32_f32_sdwa v133, v133 dst_sel:WORD_1 dst_unused:UNUSED_PAD src0_sel:DWORD
	v_cvt_i32_f32_e32 v30, v30
	v_lshlrev_b32_e32 v5, 8, v5
	v_and_b32_e32 v5, 0xff00, v5
	v_lshlrev_b32_e32 v140, 8, v140
	v_and_b32_e32 v134, 0xff0000, v134
	v_perm_b32 v4, v132, v4, s8
	v_and_b32_e32 v140, 0xff00, v140
	v_and_b32_e32 v131, 0xff0000, v133
	v_or3_b32 v4, v4, v5, v134
	v_perm_b32 v5, v30, v126, s8
	v_permlane32_swap_b32_e32 v135, v136
	v_permlane32_swap_b32_e32 v124, v125
	v_permlane32_swap_b32_e32 v96, v97
	v_permlane32_swap_b32_e32 v24, v25
	v_permlane32_swap_b32_e32 v20, v21
	v_permlane32_swap_b32_e32 v18, v19
	v_or3_b32 v5, v5, v140, v131
	v_mov_b32_e32 v202, v4
	v_mov_b32_e32 v203, v5
	global_store_dwordx4 v[2:3], v[200:203], off
	s_and_saveexec_b64 s[6:7], s[4:5]
	s_cbranch_execz .LBB0_544
	v_mov_b32_e32 v140, v160
	v_mov_b32_e32 v141, v161
	v_mov_b32_e32 v142, v162
	v_mov_b32_e32 v143, v163
	v_mov_b32_e32 v4, v141
	v_mov_b32_e32 v5, v142
	v_mov_b32_e32 v141, v143
	v_pk_add_f32 v[4:5], v[4:5], v[140:141]
	s_nop 0
	v_add_f32_e32 v4, v4, v5
	v_mov_b32_e32 v5, 0x358637bd
	v_fmac_f32_e32 v5, 0x3a800000, v4
	v_rsq_f32_e32 v4, v5
	v_mul_f32_e32 v5, 0x3c010204, v137
	v_mul_f32_e32 v4, v5, v4
	global_store_dword v31, v4, s[0:1]

.LBB0_1014:
	s_or_b64 exec, exec, s[0:1]
	s_mov_b64 s[0:1], s[82:83]
	v_mov_b32_e32 v2, v0
	s_mov_b32 s2, s73
	s_mov_b32 s5, s72
	s_barrier
	s_load_dwordx2 s[2:3], s[0:1], 0x90
	v_readfirstlane_b32 s4, v2
	s_lshl_b32 s0, s5, 3
	s_and_b32 s0, s0, 56
	s_bfe_u32 s1, s5, 0x30003
	s_ashr_i32 s4, s4, 3
	s_or_b32 s8, s0, s1
	s_and_b32 s1, s5, 0xffffffc0
	s_and_b32 s4, s4, -8
	s_lshl_b32 s0, s8, 8
	s_add_i32 s4, s1, s4
	s_add_i32 s6, s4, s0
	s_ashr_i32 s7, s6, 31
	s_lshl_b64 s[0:1], s[6:7], 11
	v_and_b32_e32 v126, 63, v2
	s_waitcnt lgkmcnt(0)
	s_add_u32 s0, s2, s0
	s_addc_u32 s1, s3, s1
	v_lshlrev_b32_e32 v30, 5, v126
	v_mov_b32_e32 v31, 0
	v_lshl_add_u64 v[2:3], s[0:1], 0, v[30:31]
	s_mov_b32 s0, 0x3001000
	v_add_co_u32_e32 v60, vcc, s0, v2
	s_mov_b64 s[0:1], 0x3000000
	s_nop 0
	v_addc_co_u32_e32 v61, vcc, 0, v3, vcc
	global_load_dwordx4 v[18:21], v[60:61], off offset:-4096
	v_lshl_add_u64 v[4:5], v[2:3], 0, s[0:1]
	global_load_dwordx4 v[22:25], v[4:5], off offset:16
	global_load_dwordx4 v[32:35], v[4:5], off offset:2048
	global_load_dwordx4 v[36:39], v[4:5], off offset:2064
	s_mov_b32 s0, 0x3002000
	v_add_co_u32_e32 v62, vcc, s0, v2
	s_mov_b32 s1, 0x3003000
	s_nop 0
	v_addc_co_u32_e32 v63, vcc, 0, v3, vcc
	v_add_co_u32_e32 v64, vcc, s1, v2
	s_lshl_b32 s5, s8, 19
	s_nop 0
	v_addc_co_u32_e32 v65, vcc, 0, v3, vcc
	global_load_dwordx4 v[40:43], v[60:61], off
	global_load_dwordx4 v[44:47], v[60:61], off offset:16
	global_load_dwordx4 v[48:51], v[60:61], off offset:2048
	global_load_dwordx4 v[52:55], v[60:61], off offset:2064
	global_load_dwordx4 v[56:59], v[64:65], off offset:-4096
	global_load_dwordx4 v[26:29], v[62:63], off offset:16
	global_load_dwordx4 v[14:17], v[62:63], off offset:2048
	global_load_dwordx4 v[10:13], v[62:63], off offset:2064
	global_load_dwordx4 v[6:9], v[64:65], off
	global_load_dwordx4 v[2:5], v[64:65], off offset:16
	s_add_u32 s5, s2, s5
	s_addc_u32 s8, s3, 0
	s_lshl_b32 s4, s4, 10
	s_and_b32 s0, s4, 0x3e000
	s_add_u32 s4, s5, s0
	s_addc_u32 s5, s8, 0
	s_mov_b32 s9, 0x42fe0000
	s_lshl_b64 s[0:1], s[6:7], 2
	s_add_u32 s0, s2, s0
	s_addc_u32 s1, s3, s1
	s_add_u32 s0, s0, 0xfc00000
	s_addc_u32 s1, s1, 0
	s_lshl_b64 s[6:7], s[6:7], 4
	s_mov_b32 s8, 0x40c0c00
	s_add_u32 s2, s2, s6
	s_mov_b32 s6, 0xa800000
	s_addc_u32 s3, s3, s7
	s_add_u32 s2, s2, 0xda00000
	s_addc_u32 s3, s3, 0
	v_mov_b32_e32 v192, 0
	global_load_dwordx4 v[160:163], v192, s[2:3]
	global_load_dwordx4 v[164:167], v192, s[2:3] offset:16
	global_load_dwordx4 v[168:171], v192, s[2:3] offset:32
	global_load_dwordx4 v[172:175], v192, s[2:3] offset:48
	global_load_dwordx4 v[176:179], v192, s[2:3] offset:64
	global_load_dwordx4 v[180:183], v192, s[2:3] offset:80
	global_load_dwordx4 v[184:187], v192, s[2:3] offset:96
	global_load_dwordx4 v[188:191], v192, s[2:3] offset:112
	s_waitcnt vmcnt(12)
	v_lshlrev_b32_e32 v148, 16, v22
	v_lshlrev_b32_e32 v140, 16, v18
	v_and_b32_e32 v141, 0xffff0000, v18
	v_lshlrev_b32_e32 v142, 16, v19
	v_and_b32_e32 v143, 0xffff0000, v19
	v_max3_f32 v18, |v140|, 0, |v141|
	v_lshlrev_b32_e32 v144, 16, v20
	v_and_b32_e32 v145, 0xffff0000, v20
	v_max3_f32 v18, v18, |v142|, |v143|
	v_lshlrev_b32_e32 v146, 16, v21
	v_and_b32_e32 v147, 0xffff0000, v21
	v_max3_f32 v18, v18, |v144|, |v145|
	v_and_b32_e32 v149, 0xffff0000, v22
	v_max3_f32 v18, v18, |v146|, |v147|
	v_lshlrev_b32_e32 v134, 16, v23
	v_and_b32_e32 v132, 0xffff0000, v23
	v_max3_f32 v18, v18, |v148|, |v149|
	v_lshlrev_b32_e32 v150, 16, v24
	v_and_b32_e32 v151, 0xffff0000, v24
	v_max3_f32 v18, v18, |v134|, |v132|
	v_lshlrev_b32_e32 v133, 16, v25
	v_and_b32_e32 v131, 0xffff0000, v25
	v_max3_f32 v18, v18, |v150|, |v151|
	v_max3_f32 v18, v18, |v133|, |v131|
	ds_swizzle_b32 v19, v18 offset:swizzle(SWAP,1)
	s_waitcnt vmcnt(11)
	v_lshlrev_b32_e32 v130, 16, v32
	v_and_b32_e32 v128, 0xffff0000, v32
	v_lshlrev_b32_e32 v122, 16, v33
	v_and_b32_e32 v119, 0xffff0000, v33
	s_waitcnt lgkmcnt(0)
	v_max_f32_e32 v19, v19, v19
	v_max_f32_e32 v18, v18, v19
	ds_swizzle_b32 v19, v18 offset:swizzle(SWAP,2)
	v_max3_f32 v20, |v130|, 0, |v128|
	v_lshlrev_b32_e32 v129, 16, v34
	v_and_b32_e32 v127, 0xffff0000, v34
	v_max3_f32 v20, v20, |v122|, |v119|
	s_waitcnt lgkmcnt(0)
	v_max_f32_e32 v19, v19, v19
	v_max_f32_e32 v18, v18, v19
	ds_swizzle_b32 v19, v18 offset:swizzle(SWAP,4)
	v_lshlrev_b32_e32 v123, 16, v35
	v_and_b32_e32 v121, 0xffff0000, v35
	v_max3_f32 v20, v20, |v129|, |v127|
	s_waitcnt vmcnt(10)
	v_lshlrev_b32_e32 v117, 16, v36
	s_waitcnt lgkmcnt(0)
	v_max_f32_e32 v19, v19, v19
	v_max_f32_e32 v18, v18, v19
	ds_swizzle_b32 v19, v18 offset:swizzle(SWAP,8)
	v_and_b32_e32 v116, 0xffff0000, v36
	v_max3_f32 v20, v20, |v123|, |v121|
	v_lshlrev_b32_e32 v113, 16, v37
	v_and_b32_e32 v114, 0xffff0000, v37
	s_waitcnt lgkmcnt(0)
	v_max_f32_e32 v19, v19, v19
	v_max_f32_e32 v30, v18, v19
	v_max3_f32 v18, v20, |v117|, |v116|
	v_lshlrev_b32_e32 v120, 16, v38
	v_and_b32_e32 v118, 0xffff0000, v38
	v_max3_f32 v18, v18, |v113|, |v114|
	v_lshlrev_b32_e32 v115, 16, v39
	v_and_b32_e32 v112, 0xffff0000, v39
	v_max3_f32 v18, v18, |v120|, |v118|
	ds_swizzle_b32 v32, v30 offset:swizzle(SWAP,16)
	v_max3_f32 v33, v18, |v115|, |v112|
	ds_swizzle_b32 v34, v33 offset:swizzle(SWAP,1)
	s_waitcnt vmcnt(9)
	v_lshlrev_b32_e32 v111, 16, v40
	v_and_b32_e32 v109, 0xffff0000, v40
	s_waitcnt lgkmcnt(1)
	v_max_f32_e32 v32, v32, v32
	v_max_f32_e32 v30, v30, v32
	s_waitcnt lgkmcnt(0)
	v_max_f32_e32 v32, v34, v34
	v_max_f32_e32 v32, v33, v32
	v_lshlrev_b32_e32 v106, 16, v41
	v_and_b32_e32 v105, 0xffff0000, v41
	v_max3_f32 v35, |v111|, 0, |v109|
	global_load_dwordx4 v[22:25], v[64:65], off offset:2048
	global_load_dwordx4 v[18:21], v[64:65], off offset:2064
	ds_swizzle_b32 v33, v32 offset:swizzle(SWAP,2)
	v_lshlrev_b32_e32 v110, 16, v42
	v_and_b32_e32 v108, 0xffff0000, v42
	v_max3_f32 v35, v35, |v106|, |v105|
	v_lshlrev_b32_e32 v107, 16, v43
	v_and_b32_e32 v104, 0xffff0000, v43
	v_max3_f32 v35, v35, |v110|, |v108|
	v_max3_f32 v35, v35, |v107|, |v104|
	s_waitcnt vmcnt(10)
	v_lshlrev_b32_e32 v103, 16, v44
	v_and_b32_e32 v101, 0xffff0000, v44
	v_lshlrev_b32_e32 v99, 16, v45
	v_and_b32_e32 v95, 0xffff0000, v45
	v_max3_f32 v35, v35, |v103|, |v101|
	v_lshlrev_b32_e32 v102, 16, v46
	v_and_b32_e32 v100, 0xffff0000, v46
	v_max3_f32 v35, v35, |v99|, |v95|
	s_waitcnt lgkmcnt(0)
	v_max_f32_e32 v33, v33, v33
	v_lshlrev_b32_e32 v98, 16, v47
	v_and_b32_e32 v94, 0xffff0000, v47
	v_max3_f32 v35, v35, |v102|, |v100|
	v_max_f32_e32 v32, v32, v33
	v_max3_f32 v35, v35, |v98|, |v94|
	ds_swizzle_b32 v33, v32 offset:swizzle(SWAP,4)
	ds_swizzle_b32 v36, v35 offset:swizzle(SWAP,1)
	v_mov_b32_e32 v34, v30
	s_nop 1
	v_permlane32_swap_b32_e32 v30, v34
	s_waitcnt lgkmcnt(1)
	v_max_f32_e32 v33, v33, v33
	s_waitcnt lgkmcnt(0)
	v_max_f32_e32 v36, v36, v36
	v_max_f32_e32 v32, v32, v33
	v_max_f32_e32 v35, v35, v36
	ds_swizzle_b32 v33, v32 offset:swizzle(SWAP,8)
	ds_swizzle_b32 v36, v35 offset:swizzle(SWAP,2)
	v_max_f32_e32 v34, v34, v34
	v_max_f32_e32 v30, v30, v30
	v_max_f32_e32 v137, v30, v34
	s_waitcnt lgkmcnt(1)
	v_max_f32_e32 v30, v33, v33
	s_waitcnt lgkmcnt(0)
	v_max_f32_e32 v33, v36, v36
	s_waitcnt vmcnt(9)
	v_lshlrev_b32_e32 v93, 16, v48
	v_and_b32_e32 v91, 0xffff0000, v48
	v_max_f32_e32 v33, v35, v33
	v_lshlrev_b32_e32 v89, 16, v49
	v_and_b32_e32 v87, 0xffff0000, v49
	v_max3_f32 v35, |v93|, 0, |v91|
	v_lshlrev_b32_e32 v92, 16, v50
	v_and_b32_e32 v90, 0xffff0000, v50
	v_max3_f32 v35, v35, |v89|, |v87|
	v_lshlrev_b32_e32 v88, 16, v51
	v_and_b32_e32 v86, 0xffff0000, v51
	v_max3_f32 v35, v35, |v92|, |v90|
	v_max3_f32 v35, v35, |v88|, |v86|
	s_waitcnt vmcnt(8)
	v_lshlrev_b32_e32 v85, 16, v52
	v_and_b32_e32 v83, 0xffff0000, v52
	v_lshlrev_b32_e32 v81, 16, v53
	v_and_b32_e32 v79, 0xffff0000, v53
	v_max3_f32 v35, v35, |v85|, |v83|
	v_lshlrev_b32_e32 v84, 16, v54
	v_and_b32_e32 v82, 0xffff0000, v54
	v_max3_f32 v35, v35, |v81|, |v79|
	v_lshlrev_b32_e32 v80, 16, v55
	v_and_b32_e32 v78, 0xffff0000, v55
	v_max3_f32 v35, v35, |v84|, |v82|
	ds_swizzle_b32 v34, v33 offset:swizzle(SWAP,4)
	v_max3_f32 v35, v35, |v80|, |v78|
	ds_swizzle_b32 v36, v35 offset:swizzle(SWAP,1)
	v_max_f32_e32 v30, v32, v30
	ds_swizzle_b32 v32, v30 offset:swizzle(SWAP,16)
	s_waitcnt lgkmcnt(2)
	v_max_f32_e32 v34, v34, v34
	v_max_f32_e32 v33, v33, v34
	s_waitcnt lgkmcnt(1)
	v_max_f32_e32 v36, v36, v36
	ds_swizzle_b32 v34, v33 offset:swizzle(SWAP,8)
	v_max_f32_e32 v35, v35, v36
	ds_swizzle_b32 v36, v35 offset:swizzle(SWAP,2)
	s_waitcnt lgkmcnt(2)
	v_max_f32_e32 v32, v32, v32
	v_max_f32_e32 v138, v30, v32
	s_waitcnt lgkmcnt(1)
	v_max_f32_e32 v30, v34, v34
	v_max_f32_e32 v30, v33, v30
	s_waitcnt lgkmcnt(0)
	v_max_f32_e32 v33, v36, v36
	s_waitcnt vmcnt(7)
	v_lshlrev_b32_e32 v77, 16, v56
	v_and_b32_e32 v75, 0xffff0000, v56
	v_max_f32_e32 v33, v35, v33
	v_lshlrev_b32_e32 v72, 16, v57
	v_and_b32_e32 v71, 0xffff0000, v57
	v_max3_f32 v35, |v77|, 0, |v75|
	v_lshlrev_b32_e32 v76, 16, v58
	v_and_b32_e32 v74, 0xffff0000, v58
	v_max3_f32 v35, v35, |v72|, |v71|
	v_lshlrev_b32_e32 v73, 16, v59
	v_and_b32_e32 v70, 0xffff0000, v59
	v_max3_f32 v35, v35, |v76|, |v74|
	v_max3_f32 v35, v35, |v73|, |v70|
	s_waitcnt vmcnt(6)
	v_lshlrev_b32_e32 v69, 16, v26
	v_and_b32_e32 v67, 0xffff0000, v26
	v_lshlrev_b32_e32 v65, 16, v27
	v_and_b32_e32 v63, 0xffff0000, v27
	v_max3_f32 v26, v35, |v69|, |v67|
	v_lshlrev_b32_e32 v68, 16, v28
	v_and_b32_e32 v66, 0xffff0000, v28
	v_max3_f32 v26, v26, |v65|, |v63|
	v_lshlrev_b32_e32 v64, 16, v29
	v_and_b32_e32 v62, 0xffff0000, v29
	v_max3_f32 v26, v26, |v68|, |v66|
	v_max3_f32 v26, v26, |v64|, |v62|
	s_waitcnt vmcnt(5)
	v_lshlrev_b32_e32 v61, 16, v14
	v_and_b32_e32 v59, 0xffff0000, v14
	ds_swizzle_b32 v27, v26 offset:swizzle(SWAP,1)
	v_lshlrev_b32_e32 v57, 16, v15
	v_and_b32_e32 v55, 0xffff0000, v15
	v_max3_f32 v14, |v61|, 0, |v59|
	v_lshlrev_b32_e32 v60, 16, v16
	v_and_b32_e32 v58, 0xffff0000, v16
	v_max3_f32 v14, v14, |v57|, |v55|
	v_lshlrev_b32_e32 v56, 16, v17
	v_and_b32_e32 v54, 0xffff0000, v17
	v_max3_f32 v14, v14, |v60|, |v58|
	v_max3_f32 v14, v14, |v56|, |v54|
	s_waitcnt vmcnt(4)
	v_lshlrev_b32_e32 v53, 16, v10
	v_and_b32_e32 v51, 0xffff0000, v10
	v_lshlrev_b32_e32 v49, 16, v11
	v_and_b32_e32 v47, 0xffff0000, v11
	v_max3_f32 v10, v14, |v53|, |v51|
	s_waitcnt lgkmcnt(0)
	v_max_f32_e32 v27, v27, v27
	v_lshlrev_b32_e32 v52, 16, v12
	v_and_b32_e32 v50, 0xffff0000, v12
	v_max3_f32 v10, v10, |v49|, |v47|
	v_max_f32_e32 v26, v26, v27
	v_lshlrev_b32_e32 v48, 16, v13
	v_and_b32_e32 v46, 0xffff0000, v13
	v_max3_f32 v10, v10, |v52|, |v50|
	ds_swizzle_b32 v27, v26 offset:swizzle(SWAP,2)
	v_max3_f32 v10, v10, |v48|, |v46|
	ds_swizzle_b32 v11, v10 offset:swizzle(SWAP,1)
	ds_swizzle_b32 v34, v33 offset:swizzle(SWAP,4)
	ds_swizzle_b32 v32, v30 offset:swizzle(SWAP,16)
	s_waitcnt lgkmcnt(3)
	v_max_f32_e32 v27, v27, v27
	v_max_f32_e32 v26, v26, v27
	s_waitcnt lgkmcnt(2)
	v_max_f32_e32 v11, v11, v11
	ds_swizzle_b32 v27, v26 offset:swizzle(SWAP,4)
	v_max_f32_e32 v10, v10, v11
	ds_swizzle_b32 v11, v10 offset:swizzle(SWAP,2)
	s_waitcnt lgkmcnt(3)
	v_max_f32_e32 v34, v34, v34
	v_max_f32_e32 v33, v33, v34
	ds_swizzle_b32 v34, v33 offset:swizzle(SWAP,8)
	s_waitcnt lgkmcnt(2)
	v_max_f32_e32 v12, v27, v27
	v_max_f32_e32 v12, v26, v12
	s_waitcnt lgkmcnt(1)
	v_max_f32_e32 v11, v11, v11
	ds_swizzle_b32 v13, v12 offset:swizzle(SWAP,8)
	v_max_f32_e32 v10, v10, v11
	ds_swizzle_b32 v11, v10 offset:swizzle(SWAP,4)
	s_waitcnt lgkmcnt(2)
	v_max_f32_e32 v28, v34, v34
	v_max_f32_e32 v28, v33, v28
	ds_swizzle_b32 v29, v28 offset:swizzle(SWAP,16)
	s_waitcnt lgkmcnt(2)
	v_max_f32_e32 v13, v13, v13
	v_max_f32_e32 v12, v12, v13
	s_waitcnt lgkmcnt(1)
	v_max_f32_e32 v11, v11, v11
	ds_swizzle_b32 v13, v12 offset:swizzle(SWAP,16)
	v_max_f32_e32 v10, v10, v11
	ds_swizzle_b32 v11, v10 offset:swizzle(SWAP,8)
	s_waitcnt vmcnt(3)
	v_lshlrev_b32_e32 v45, 16, v6
	v_and_b32_e32 v43, 0xffff0000, v6
	v_max_f32_e32 v32, v32, v32
	s_waitcnt lgkmcnt(2)
	v_max_f32_e32 v29, v29, v29
	v_lshlrev_b32_e32 v40, 16, v7
	v_and_b32_e32 v39, 0xffff0000, v7
	v_max3_f32 v6, |v45|, 0, |v43|
	s_waitcnt vmcnt(1)
	v_lshlrev_b32_e32 v27, 16, v22
	v_and_b32_e32 v26, 0xffff0000, v22
	v_max_f32_e32 v135, v30, v32
	v_max_f32_e32 v124, v28, v29
	v_lshlrev_b32_e32 v44, 16, v8
	v_and_b32_e32 v42, 0xffff0000, v8
	v_max3_f32 v6, v6, |v40|, |v39|
	v_lshlrev_b32_e32 v32, 16, v5
	v_and_b32_e32 v28, 0xffff0000, v5
	v_lshlrev_b32_e32 v17, 16, v23
	v_and_b32_e32 v15, 0xffff0000, v23
	v_max3_f32 v5, |v27|, 0, |v26|
	v_lshlrev_b32_e32 v41, 16, v9
	v_and_b32_e32 v38, 0xffff0000, v9
	v_max3_f32 v6, v6, |v44|, |v42|
	v_lshlrev_b32_e32 v23, 16, v24
	v_and_b32_e32 v22, 0xffff0000, v24
	v_max3_f32 v5, v5, |v17|, |v15|
	s_waitcnt lgkmcnt(1)
	v_max_f32_e32 v13, v13, v13
	v_max3_f32 v6, v6, |v41|, |v38|
	v_lshlrev_b32_e32 v37, 16, v2
	v_and_b32_e32 v35, 0xffff0000, v2
	v_lshlrev_b32_e32 v16, 16, v25
	v_and_b32_e32 v14, 0xffff0000, v25
	v_max3_f32 v5, v5, |v23|, |v22|
	v_max_f32_e32 v96, v12, v13
	v_lshlrev_b32_e32 v33, 16, v3
	v_and_b32_e32 v29, 0xffff0000, v3
	v_lshlrev_b32_e32 v36, 16, v4
	v_and_b32_e32 v34, 0xffff0000, v4
	v_max3_f32 v2, v6, |v37|, |v35|
	s_waitcnt lgkmcnt(0)
	v_max_f32_e32 v4, v11, v11
	v_max3_f32 v5, v5, |v16|, |v14|
	s_waitcnt vmcnt(0)
	v_lshlrev_b32_e32 v13, 16, v18
	v_and_b32_e32 v11, 0xffff0000, v18
	v_max3_f32 v2, v2, |v33|, |v29|
	v_lshlrev_b32_e32 v9, 16, v19
	v_and_b32_e32 v7, 0xffff0000, v19
	v_max3_f32 v5, v5, |v13|, |v11|
	v_max3_f32 v2, v2, |v36|, |v34|
	v_max_f32_e32 v4, v10, v4
	v_lshlrev_b32_e32 v12, 16, v20
	v_and_b32_e32 v10, 0xffff0000, v20
	v_max3_f32 v5, v5, |v9|, |v7|
	v_max3_f32 v2, v2, |v32|, |v28|
	v_lshlrev_b32_e32 v8, 16, v21
	v_and_b32_e32 v6, 0xffff0000, v21
	v_max3_f32 v5, v5, |v12|, |v10|
	ds_swizzle_b32 v3, v2 offset:swizzle(SWAP,1)
	v_max3_f32 v5, v5, |v8|, |v6|
	ds_swizzle_b32 v18, v5 offset:swizzle(SWAP,1)
	ds_swizzle_b32 v19, v4 offset:swizzle(SWAP,16)
	v_lshlrev_b32_e32 v30, 4, v126
	s_waitcnt lgkmcnt(2)
	v_max_f32_e32 v3, v3, v3
	v_max_f32_e32 v2, v2, v3
	s_waitcnt lgkmcnt(1)
	v_max_f32_e32 v18, v18, v18
	ds_swizzle_b32 v3, v2 offset:swizzle(SWAP,2)
	v_max_f32_e32 v5, v5, v18
	ds_swizzle_b32 v18, v5 offset:swizzle(SWAP,2)
	s_waitcnt lgkmcnt(2)
	v_max_f32_e32 v19, v19, v19
	v_max_f32_e32 v24, v4, v19
	s_waitcnt lgkmcnt(1)
	v_max_f32_e32 v3, v3, v3
	v_max_f32_e32 v2, v2, v3
	s_waitcnt lgkmcnt(0)
	v_max_f32_e32 v18, v18, v18
	ds_swizzle_b32 v3, v2 offset:swizzle(SWAP,4)
	v_max_f32_e32 v5, v5, v18
	ds_swizzle_b32 v18, v5 offset:swizzle(SWAP,4)
	v_mov_b32_e32 v139, v138
	v_mov_b32_e32 v136, v135
	s_waitcnt lgkmcnt(1)
	v_max_f32_e32 v3, v3, v3
	v_max_f32_e32 v2, v2, v3
	s_waitcnt lgkmcnt(0)
	v_max_f32_e32 v4, v18, v18
	ds_swizzle_b32 v3, v2 offset:swizzle(SWAP,8)
	v_max_f32_e32 v4, v5, v4
	ds_swizzle_b32 v5, v4 offset:swizzle(SWAP,8)
	v_mov_b32_e32 v125, v124
	v_mov_b32_e32 v97, v96
	s_waitcnt lgkmcnt(1)
	v_max_f32_e32 v3, v3, v3
	v_max_f32_e32 v2, v2, v3
	s_waitcnt lgkmcnt(0)
	v_max_f32_e32 v5, v5, v5
	ds_swizzle_b32 v3, v2 offset:swizzle(SWAP,16)
	v_max_f32_e32 v4, v4, v5
	ds_swizzle_b32 v5, v4 offset:swizzle(SWAP,16)
	v_mov_b32_e32 v25, v24
	v_permlane32_swap_b32_e32 v138, v139
	s_waitcnt lgkmcnt(1)
	v_max_f32_e32 v3, v3, v3
	v_max_f32_e32 v20, v2, v3
	s_waitcnt lgkmcnt(0)
	v_max_f32_e32 v2, v5, v5
	v_max_f32_e32 v18, v4, v2
	v_lshl_add_u64 v[4:5], s[4:5], 0, v[30:31]
	v_div_scale_f32 v30, s[4:5], v137, v137, s9
	v_rcp_f32_e32 v152, v30
	s_mov_b64 s[4:5], 0xa800000
	v_lshl_add_u64 v[2:3], v[4:5], 0, s[4:5]
	v_cmp_eq_u32_e64 s[4:5], 0, v126
	v_fma_f32 v126, -v30, v152, 1.0
	v_fmac_f32_e32 v152, v126, v152
	v_div_scale_f32 v126, vcc, s9, v137, s9
	v_mul_f32_e32 v153, v126, v152
	v_fma_f32 v154, -v30, v153, v126
	v_fmac_f32_e32 v153, v154, v152
	v_fma_f32 v30, -v30, v153, v126
	v_div_fmas_f32 v30, v30, v152, v153
	v_div_fixup_f32 v30, v30, v137, s9
	v_cmp_lt_f32_e32 vcc, 0, v137
	v_mov_b32_e32 v21, v20
	v_mov_b32_e32 v19, v18
	v_cndmask_b32_e32 v30, 0, v30, vcc
	v_mul_f32_e32 v126, v30, v140
	v_mul_f32_e32 v140, v30, v141
	v_rndne_f32_e32 v140, v140
	v_mul_f32_e32 v141, v30, v144
	v_mul_f32_e32 v144, v30, v145
	v_mul_f32_e32 v142, v30, v142
	v_mul_f32_e32 v143, v30, v143
	v_rndne_f32_e32 v126, v126
	v_cvt_i32_f32_e32 v140, v140
	v_rndne_f32_e32 v144, v144
	v_rndne_f32_e32 v142, v142
	v_mul_f32_e32 v145, v30, v146
	v_rndne_f32_e32 v143, v143
	v_mul_f32_e32 v146, v30, v147
	v_cvt_i32_f32_e32 v126, v126
	v_rndne_f32_e32 v141, v141
	v_cvt_i32_f32_e32 v144, v144
	v_cvt_i32_f32_sdwa v142, v142 dst_sel:WORD_1 dst_unused:UNUSED_PAD src0_sel:DWORD
	v_rndne_f32_e32 v145, v145
	v_cvt_i32_f32_e32 v143, v143
	v_rndne_f32_e32 v146, v146
	v_cvt_i32_f32_e32 v141, v141
	v_cvt_i32_f32_sdwa v145, v145 dst_sel:WORD_1 dst_unused:UNUSED_PAD src0_sel:DWORD
	v_cvt_i32_f32_e32 v146, v146
	v_lshlrev_b32_e32 v140, 8, v140
	v_and_b32_e32 v140, 0xff00, v140
	v_lshlrev_b32_e32 v144, 8, v144
	v_and_b32_e32 v142, 0xff0000, v142
	v_perm_b32 v126, v143, v126, s8
	v_and_b32_e32 v144, 0xff00, v144
	v_and_b32_e32 v145, 0xff0000, v145
	v_or3_b32 v140, v126, v140, v142
	v_perm_b32 v126, v146, v141, s8
	v_add_co_u32_e32 v4, vcc, s6, v4
	v_or3_b32 v141, v126, v144, v145
	s_nop 0
	v_addc_co_u32_e32 v5, vcc, 0, v5, vcc
	v_mov_b32_e32 v200, v140
	v_mov_b32_e32 v201, v141
	v_mul_f32_e32 v5, v30, v149
	v_mul_f32_e32 v4, v30, v148
	v_rndne_f32_e32 v5, v5
	v_mul_f32_e32 v140, v30, v151
	v_mul_f32_e32 v134, v30, v134
	v_mul_f32_e32 v132, v30, v132
	v_rndne_f32_e32 v4, v4
	v_cvt_i32_f32_e32 v5, v5
	v_mul_f32_e32 v126, v30, v150
	v_rndne_f32_e32 v140, v140
	v_rndne_f32_e32 v134, v134
	v_mul_f32_e32 v133, v30, v133
	v_rndne_f32_e32 v132, v132
	v_mul_f32_e32 v30, v30, v131
	v_cvt_i32_f32_e32 v4, v4
	v_rndne_f32_e32 v126, v126
	v_cvt_i32_f32_e32 v140, v140
	v_cvt_i32_f32_sdwa v134, v134 dst_sel:WORD_1 dst_unused:UNUSED_PAD src0_sel:DWORD
	v_rndne_f32_e32 v133, v133
	v_cvt_i32_f32_e32 v132, v132
	v_rndne_f32_e32 v30, v30
	v_cvt_i32_f32_e32 v126, v126
	v_cvt_i32_f32_sdwa v133, v133 dst_sel:WORD_1 dst_unused:UNUSED_PAD src0_sel:DWORD
	v_cvt_i32_f32_e32 v30, v30
	v_lshlrev_b32_e32 v5, 8, v5
	v_and_b32_e32 v5, 0xff00, v5
	v_lshlrev_b32_e32 v140, 8, v140
	v_and_b32_e32 v134, 0xff0000, v134
	v_perm_b32 v4, v132, v4, s8
	v_and_b32_e32 v140, 0xff00, v140
	v_and_b32_e32 v131, 0xff0000, v133
	v_or3_b32 v4, v4, v5, v134
	v_perm_b32 v5, v30, v126, s8
	v_permlane32_swap_b32_e32 v135, v136
	v_permlane32_swap_b32_e32 v124, v125
	v_permlane32_swap_b32_e32 v96, v97
	v_permlane32_swap_b32_e32 v24, v25
	v_permlane32_swap_b32_e32 v20, v21
	v_permlane32_swap_b32_e32 v18, v19
	v_or3_b32 v5, v5, v140, v131
	v_mov_b32_e32 v202, v4
	v_mov_b32_e32 v203, v5
	global_store_dwordx4 v[2:3], v[200:203], off
	s_and_saveexec_b64 s[6:7], s[4:5]
	s_cbranch_execz .LBB0_1016
	v_mov_b32_e32 v140, v160
	v_mov_b32_e32 v141, v161
	v_mov_b32_e32 v142, v162
	v_mov_b32_e32 v143, v163
	v_mov_b32_e32 v4, v141
	v_mov_b32_e32 v5, v142
	v_mov_b32_e32 v141, v143
	v_pk_add_f32 v[4:5], v[4:5], v[140:141]
	s_nop 0
	v_add_f32_e32 v4, v4, v5
	v_mov_b32_e32 v5, 0x358637bd
	v_fmac_f32_e32 v5, 0x3a800000, v4
	v_rsq_f32_e32 v4, v5
	v_mul_f32_e32 v5, 0x3c010204, v137
	v_mul_f32_e32 v4, v5, v4
	global_store_dword v31, v4, s[0:1]
